# speedup vs baseline: 1.0196x; 1.0063x over previous
; __device__ __forceinline__ unsigned pk2(float lo, float hi) { return pg8::cvt_pk_bf16(lo, hi); }
; __device__ __forceinline__ float bflo(unsigned w) { return __uint_as_float(w << 16); }
; __device__ __forceinline__ float bfhi(unsigned w) { return __uint_as_float(w & 0xffff0000u); }
; __device__ __forceinline__ void phase_mix(KA a, int l, LAS unsigned char* lds, int vcu, int G, int wave) {
;     ...
;     for (int t = gw; t < T_; t += NGW) {
;         const bf16* row = (const bf16*)(a->ws + WS_AO) + (size_t)t * 1024;
;         float v[16]; float ss = 0.f;
;         if (t < 8192) {
;             u32x4 x[2]; x[0] = *(const u32x4*)(row + lane * 8); x[1] = *(const u32x4*)(row + 512 + lane * 8);
; #pragma unroll
;             for (int j = 0; j < 2; ++j) { v[j * 8 + 0] = bflo(x[j].x); v[j * 8 + 1] = bfhi(x[j].x); v[j * 8 + 2] = bflo(x[j].y); v[j * 8 + 3] = bfhi(x[j].y);
;                 v[j * 8 + 4] = bflo(x[j].z); v[j * 8 + 5] = bfhi(x[j].z); v[j * 8 + 6] = bflo(x[j].w); v[j * 8 + 7] = bfhi(x[j].w); }
;     ...
;         for (int j = 0; j < 2; ++j) { const float* g = ga + j * 512 + lane * 8; u32x4 w;
;             w.x = pk2(v[j * 8 + 0] * rs * g[0], v[j * 8 + 1] * rs * g[1]); w.y = pk2(v[j * 8 + 2] * rs * g[2], v[j * 8 + 3] * rs * g[3]);
;             w.z = pk2(v[j * 8 + 4] * rs * g[4], v[j * 8 + 5] * rs * g[5]); w.w = pk2(v[j * 8 + 6] * rs * g[6], v[j * 8 + 7] * rs * g[7]);
;             *(u32x4*)(MIX + (size_t)t * 2048 + j * 512 + lane * 8) = w; }
.LBB0_130:
	s_and_b64 vcc, exec, s[22:23]
	s_cbranch_vccz .LBB0_159
	v_readlane_b32 s0, v254, 62
	s_lshl_b32 s5, s81, 8
	s_add_i32 s5, s5, s11
	s_sub_i32 s5, s5, s81
	s_lshl_b32 s42, s0, 10
	v_mbcnt_lo_u32_b32 v26, -1, 0
	v_mbcnt_hi_u32_b32 v26, -1, v26
	s_load_dwordx2 s[48:49], s[36:37], 0xa8
	s_add_i32 s44, s5, s81
	s_ashr_i32 s43, s42, 31
	s_add_u32 s40, s16, 0x20c90000
	s_addc_u32 s41, s17, 0
	v_and_b32_e32 v27, 63, v26
	s_cmpk_lt_i32 s44, 0x2010
	v_lshlrev_b32_e32 v148, 5, v27
	s_waitcnt vmcnt(0)
	v_lshlrev_b32_e32 v8, 4, v27
	s_cbranch_scc0 .LBB0_142
	s_load_dwordx2 s[18:19], s[36:37], 0xa0
	s_lshl_b32 s7, s15, 3
	s_add_u32 s52, s16, 0x2f3a0000
	s_addc_u32 s53, s17, 0
	s_lshl_b64 s[20:21], s[42:43], 2
	s_waitcnt lgkmcnt(0)
	s_add_u32 s18, s18, s20
	s_addc_u32 s19, s19, s21
	v_lshrrev_b32_e32 v2, 4, v27
	v_mov_b32_e32 v9, v149
	v_mov_b32_e32 v0, 0x840
	s_movk_i32 s1, 0x210
	v_lshl_add_u64 v[10:11], s[18:19], 0, v[148:149]
	v_mad_u32_u24 v29, v2, s1, v0
	v_lshl_add_u64 v[0:1], s[16:17], 0, v[8:9]
	s_mov_b64 s[18:19], 0x1eb90000
	v_lshl_add_u64 v[14:15], v[0:1], 0, s[18:19]
	v_and_b32_e32 v0, 15, v26
	v_readlane_b32 s0, v254, 43
	v_lshlrev_b32_e32 v0, 5, v0
	v_mov_b32_e32 v1, v149
	s_add_i32 s3, s5, s0
	v_readlane_b32 s0, v254, 44
	v_lshl_add_u64 v[16:17], s[16:17], 0, v[0:1]
	v_mov_b32_e32 v0, s3
	s_add_i32 s3, s5, s0
	v_lshl_add_u64 v[12:13], s[40:41], 0, v[8:9]
	v_mad_u32_u24 v9, v2, s1, v0
	v_mov_b32_e32 v0, s3
	v_mul_u32_u24_e32 v28, 0x210, v2
	v_mad_u32_u24 v30, v2, s1, v0
	global_load_dwordx2 v[232:233], v[10:11], off
	global_load_dwordx2 v[234:235], v[10:11], off offset:8
	global_load_dwordx2 v[236:237], v[10:11], off offset:16
	global_load_dwordx2 v[238:239], v[10:11], off offset:24
	global_load_dwordx2 v[240:241], v[10:11], off offset:2048
	global_load_dwordx2 v[242:243], v[10:11], off offset:2056
	global_load_dwordx2 v[244:245], v[10:11], off offset:2064
	global_load_dwordx2 v[246:247], v[10:11], off offset:2072
	s_add_i32 s18, s44, 0x0
	s_mov_b32 s19, 0
	s_lshl_b64 s[18:19], s[18:19], 11
	v_lshl_add_u64 v[104:105], v[14:15], 0, s[18:19]
	global_load_dwordx4 v[72:75], v[104:105], off
	global_load_dwordx4 v[76:79], v[104:105], off offset:1024
	s_add_i32 s18, s44, 0x800
	s_mov_b32 s19, 0
	s_lshl_b64 s[18:19], s[18:19], 11
	v_lshl_add_u64 v[104:105], v[14:15], 0, s[18:19]
	global_load_dwordx4 v[80:83], v[104:105], off
	global_load_dwordx4 v[84:87], v[104:105], off offset:1024
	s_add_i32 s18, s44, 0x1000
	s_mov_b32 s19, 0
	s_lshl_b64 s[18:19], s[18:19], 11
	v_lshl_add_u64 v[104:105], v[14:15], 0, s[18:19]
	global_load_dwordx4 v[88:91], v[104:105], off
	global_load_dwordx4 v[92:95], v[104:105], off offset:1024
	s_add_i32 s18, s44, 0x1800
	s_mov_b32 s19, 0
	s_lshl_b64 s[18:19], s[18:19], 11
	v_lshl_add_u64 v[104:105], v[14:15], 0, s[18:19]
	global_load_dwordx4 v[96:99], v[104:105], off
	global_load_dwordx4 v[100:103], v[104:105], off offset:1024
	s_branch .LBB0_134

; __device__ __forceinline__ float bflo(unsigned w) { return __uint_as_float(w << 16); }
; __device__ __forceinline__ float bfhi(unsigned w) { return __uint_as_float(w & 0xffff0000u); }
; __device__ __forceinline__ void phase_mix(KA a, int l, LAS unsigned char* lds, int vcu, int G, int wave) {
;     ...
;         if (t < 8192) {
;             u32x4 x[2]; x[0] = *(const u32x4*)(row + lane * 8); x[1] = *(const u32x4*)(row + 512 + lane * 8);
; #pragma unroll
;             for (int j = 0; j < 2; ++j) { v[j * 8 + 0] = bflo(x[j].x); v[j * 8 + 1] = bfhi(x[j].x); v[j * 8 + 2] = bflo(x[j].y); v[j * 8 + 3] = bfhi(x[j].y);
;                 v[j * 8 + 4] = bflo(x[j].z); v[j * 8 + 5] = bfhi(x[j].z); v[j * 8 + 6] = bflo(x[j].w); v[j * 8 + 7] = bfhi(x[j].w); }
.LBB0_140:
	s_and_b64 vcc, exec, s[22:23]
	s_cbranch_vccz .LBB0_133
	s_waitcnt vmcnt(0)
	v_mov_b32_e32 v0, v72
	v_mov_b32_e32 v1, v73
	v_mov_b32_e32 v2, v74
	v_mov_b32_e32 v3, v75
	v_mov_b32_e32 v4, v76
	v_mov_b32_e32 v5, v77
	v_mov_b32_e32 v6, v78
	v_mov_b32_e32 v7, v79
	v_mov_b32_e32 v72, v80
	v_mov_b32_e32 v73, v81
	v_mov_b32_e32 v74, v82
	v_mov_b32_e32 v75, v83
	v_mov_b32_e32 v76, v84
	v_mov_b32_e32 v77, v85
	v_mov_b32_e32 v78, v86
	v_mov_b32_e32 v79, v87
	v_mov_b32_e32 v80, v88
	v_mov_b32_e32 v81, v89
	v_mov_b32_e32 v82, v90
	v_mov_b32_e32 v83, v91
	v_mov_b32_e32 v84, v92
	v_mov_b32_e32 v85, v93
	v_mov_b32_e32 v86, v94
	v_mov_b32_e32 v87, v95
	v_mov_b32_e32 v88, v96
	v_mov_b32_e32 v89, v97
	v_mov_b32_e32 v90, v98
	v_mov_b32_e32 v91, v99
	v_mov_b32_e32 v92, v100
	v_mov_b32_e32 v93, v101
	v_mov_b32_e32 v94, v102
	v_mov_b32_e32 v95, v103
	v_and_b32_e32 v36, 0xffff0000, v0
	v_and_b32_e32 v37, 0xffff0000, v1
	v_and_b32_e32 v32, 0xffff0000, v2
	v_and_b32_e32 v31, 0xffff0000, v3
	v_and_b32_e32 v24, 0xffff0000, v4
	v_and_b32_e32 v22, 0xffff0000, v5
	v_and_b32_e32 v20, 0xffff0000, v6
	v_and_b32_e32 v18, 0xffff0000, v7
	s_branch .LBB0_133

; #define LAS __attribute__((address_space(3)))
; __device__ __forceinline__ float bflo(unsigned w) { return __uint_as_float(w << 16); }
; __device__ __forceinline__ float bfhi(unsigned w) { return __uint_as_float(w & 0xffff0000u); }
; __device__ __forceinline__ void phase_attn_tail(KA a, LAS unsigned char* lds, int vcu, int G, int wave) {
;     ...
;             if (j < nk) {
;                 const bf16* kr = K + ((size_t)h * TP + k0 + j) * QKD;
; #pragma unroll 2
;                 for (int d = 0; d < QKD; d += 8) {
;                     const u32x4 kk = *(const u32x4*)(kr + d);
;                     const float k8[8] = {bflo(kk.x), bfhi(kk.x), bflo(kk.y), bfhi(kk.y), bflo(kk.z), bfhi(kk.z), bflo(kk.w), bfhi(kk.w)};
; #pragma unroll
;                     for (int i = 0; i < 8; ++i) { const f32x4 q0 = *(const LAS f32x4*)(qs + (half * 8 + i) * 192 + d), q1 = *(const LAS f32x4*)(qs + (half * 8 + i) * 192 + d + 4);
;                         sv[i] += q0.x * k8[0] + q0.y * k8[1] + q0.z * k8[2] + q0.w * k8[3] + q1.x * k8[4] + q1.y * k8[5] + q1.z * k8[6] + q1.w * k8[7]; }
;                 }
.LBB0_212:
	s_or_b64 exec, exec, s[54:55]
	s_and_b32 s3, s11, 31
	s_and_b64 s[18:19], s[22:23], exec
	s_cselect_b32 s20, 0x100, 16
	v_mov_b32_e32 v25, 0
	s_cselect_b32 s24, s3, 32
	v_cmp_gt_u32_e32 vcc, s20, v14
	v_mov_b32_e32 v24, v25
	v_mov_b32_e32 v27, v25
	v_mov_b32_e32 v26, v25
	v_mov_b32_e32 v29, v25
	v_mov_b32_e32 v28, v25
	v_mov_b32_e32 v31, v25
	v_mov_b32_e32 v30, v25
	s_waitcnt vmcnt(0) lgkmcnt(0)
	s_barrier
	s_and_saveexec_b64 s[54:55], vcc
	s_cbranch_execz .LBB0_215
	s_lshl_b32 s3, s24, 8
	s_mul_i32 s18, s21, 0x2100
	s_add_u32 s3, s18, s3
	s_mul_hi_i32 s5, s21, 0x2100
	v_or_b32_e32 v2, s3, v14
	v_mov_b64_e32 v[0:1], s[52:53]
	s_addc_u32 s5, s5, 0
	v_mad_u64_u32 v[22:23], s[18:19], v2, s26, v[0:1]
	v_mov_b32_e32 v0, 0x180
	v_mov_b32_e32 v24, 0
	v_mad_i32_i24 v23, s5, v0, v23
	s_mov_b32 s18, -8
	v_mov_b32_e32 v39, v33
	v_mov_b32_e32 v25, v24
	v_mov_b32_e32 v30, v24
	v_mov_b32_e32 v31, v24
	v_mov_b32_e32 v28, v24
	v_mov_b32_e32 v29, v24
	v_mov_b32_e32 v26, v24
	v_mov_b32_e32 v27, v24
	global_load_dwordx4 v[120:123], v[22:23], off
	global_load_dwordx4 v[124:127], v[22:23], off offset:-16
.LBB0_214:
	ds_read_b128 v[44:47], v39
	ds_read_b128 v[48:51], v39 offset:16
	ds_read_b128 v[4:7], v39 offset:32
	ds_read_b128 v[0:3], v39 offset:48
	ds_read_b128 v[52:55], v39 offset:768
	ds_read_b128 v[56:59], v39 offset:784
	ds_read_b128 v[60:63], v39 offset:1536
	ds_read_b128 v[64:67], v39 offset:1552
	ds_read_b128 v[68:71], v39 offset:2304
	ds_read_b128 v[72:75], v39 offset:2320
	ds_read_b128 v[76:79], v39 offset:3072
	ds_read_b128 v[80:83], v39 offset:3088
	ds_read_b128 v[84:87], v39 offset:3840
	ds_read_b128 v[88:91], v39 offset:3856
	ds_read_b128 v[92:95], v39 offset:4608
	ds_read_b128 v[96:99], v39 offset:4624
	ds_read_b128 v[100:103], v39 offset:5376
	ds_read_b128 v[104:107], v39 offset:5392
	s_waitcnt lgkmcnt(13)
	v_pk_mov_b32 v[116:117], v[44:45], v[52:53] op_sel:[1,0]
	v_mov_b32_e32 v45, v53
	v_mov_b32_e32 v52, v46
	v_mov_b32_e32 v53, v54
	v_mov_b32_e32 v54, v47
	v_mov_b32_e32 v46, v48
	s_waitcnt lgkmcnt(12)
	v_mov_b32_e32 v47, v56
	v_mov_b32_e32 v56, v49
	s_add_i32 s18, s18, 16
	v_lshl_add_u64 v[22:23], v[22:23], 0, 32
	s_cmpk_lt_u32 s18, 0xb8
	s_waitcnt vmcnt(0)
	v_mov_b32_e32 v8, v120
	v_mov_b32_e32 v9, v121
	v_mov_b32_e32 v10, v122
	v_mov_b32_e32 v11, v123
	v_mov_b32_e32 v40, v124
	v_mov_b32_e32 v41, v125
	v_mov_b32_e32 v42, v126
	v_mov_b32_e32 v43, v127
	global_load_dwordx4 v[120:123], v[22:23], off
	global_load_dwordx4 v[124:127], v[22:23], off offset:-16
	v_and_b32_e32 v111, 0xffff0000, v40
	v_lshlrev_b32_e32 v108, 16, v40
	v_and_b32_e32 v110, 16, v40
	v_mov_b32_e32 v109, v111
	s_waitcnt lgkmcnt(3)
	v_mul_f32_e32 v40, v93, v111
	v_pk_mov_b32 v[110:111], v[110:111], v[108:109] op_sel:[1,0]
	v_pk_mul_f32 v[44:45], v[44:45], v[108:109]
	v_pk_fma_f32 v[92:93], v[92:93], v[108:109], v[40:41] op_sel_hi:[1,1,0]
	s_waitcnt lgkmcnt(1)
	v_mul_f32_e32 v40, v100, v108
	v_and_b32_e32 v113, 0xffff0000, v41
	v_lshlrev_b32_e32 v112, 16, v41
	v_pk_fma_f32 v[44:45], v[116:117], v[110:111], v[44:45]
	v_pk_fma_f32 v[100:101], v[100:101], v[108:109], v[40:41] op_sel_hi:[1,1,0]
	v_pk_fma_f32 v[44:45], v[52:53], v[112:113], v[44:45] op_sel_hi:[1,0,1]
	v_mul_f32_e32 v100, v94, v112
	v_mul_f32_e32 v40, v95, v113
	v_pk_mul_f32 v[94:95], v[102:103], v[112:113]
	v_and_b32_e32 v103, 0xffff0000, v42
	v_lshlrev_b32_e32 v102, 16, v42
	v_pk_fma_f32 v[44:45], v[54:55], v[112:113], v[44:45] op_sel:[0,1,0]
	v_and_b32_e32 v115, 0xffff0000, v43
	v_pk_fma_f32 v[44:45], v[46:47], v[102:103], v[44:45] op_sel_hi:[1,0,1]
	v_lshlrev_b32_e32 v114, 16, v43
	v_pk_fma_f32 v[44:45], v[56:57], v[102:103], v[44:45] op_sel:[0,1,0]
	v_mov_b32_e32 v46, v50
	v_mov_b32_e32 v47, v58
	v_pk_fma_f32 v[44:45], v[46:47], v[114:115], v[44:45] op_sel_hi:[1,0,1]
	v_mov_b32_e32 v58, v51
	v_pk_fma_f32 v[44:45], v[58:59], v[114:115], v[44:45] op_sel:[0,1,0]
	v_mov_b32_e32 v93, v94
	v_pk_add_f32 v[30:31], v[30:31], v[44:45]
	v_pk_mov_b32 v[44:45], v[60:61], v[68:69] op_sel:[1,0]
	v_mov_b32_e32 v61, v69
	v_pk_mul_f32 v[46:47], v[60:61], v[108:109]
	s_waitcnt lgkmcnt(0)
; #define LAS __attribute__((address_space(3)))
; __device__ __forceinline__ float bflo(unsigned w) { return __uint_as_float(w << 16); }
; __device__ __forceinline__ float bfhi(unsigned w) { return __uint_as_float(w & 0xffff0000u); }
; __device__ __forceinline__ void phase_attn_tail(KA a, LAS unsigned char* lds, int vcu, int G, int wave) {
;     ...
;                 for (int d = 0; d < QKD; d += 8) {
;                     const u32x4 kk = *(const u32x4*)(kr + d);
;                     const float k8[8] = {bflo(kk.x), bfhi(kk.x), bflo(kk.y), bfhi(kk.y), bflo(kk.z), bfhi(kk.z), bflo(kk.w), bfhi(kk.w)};
; #pragma unroll
;                     for (int i = 0; i < 8; ++i) { const f32x4 q0 = *(const LAS f32x4*)(qs + (half * 8 + i) * 192 + d), q1 = *(const LAS f32x4*)(qs + (half * 8 + i) * 192 + d + 4);
;                         sv[i] += q0.x * k8[0] + q0.y * k8[1] + q0.z * k8[2] + q0.w * k8[3] + q1.x * k8[4] + q1.y * k8[5] + q1.z * k8[6] + q1.w * k8[7]; }
;                 }
;             }
; #pragma unroll
;             for (int i = 0; i < 8; ++i) sc[(half * 8 + i) * 256 + j] = j < nk ? sv[i] * C : -1e30f;
	v_pk_mul_f32 v[104:105], v[104:105], v[102:103]
	v_pk_fma_f32 v[44:45], v[44:45], v[110:111], v[46:47]
	v_mov_b32_e32 v46, v62
	v_mov_b32_e32 v47, v70
	v_pk_fma_f32 v[44:45], v[46:47], v[112:113], v[44:45] op_sel_hi:[1,0,1]
	v_mov_b32_e32 v70, v63
	v_pk_fma_f32 v[44:45], v[70:71], v[112:113], v[44:45] op_sel:[0,1,0]
	v_mov_b32_e32 v46, v64
	v_mov_b32_e32 v47, v72
	v_pk_fma_f32 v[44:45], v[46:47], v[102:103], v[44:45] op_sel_hi:[1,0,1]
	v_mov_b32_e32 v72, v65
	v_pk_fma_f32 v[44:45], v[72:73], v[102:103], v[44:45] op_sel:[0,1,0]
	v_mov_b32_e32 v46, v66
	v_mov_b32_e32 v47, v74
	v_pk_fma_f32 v[44:45], v[46:47], v[114:115], v[44:45] op_sel_hi:[1,0,1]
	v_mov_b32_e32 v74, v67
	v_pk_fma_f32 v[44:45], v[74:75], v[114:115], v[44:45] op_sel:[0,1,0]
	v_pk_add_f32 v[50:51], v[92:93], v[100:101]
	v_pk_add_f32 v[28:29], v[28:29], v[44:45]
	v_pk_mov_b32 v[44:45], v[76:77], v[84:85] op_sel:[1,0]
	v_mov_b32_e32 v77, v85
	v_pk_mul_f32 v[46:47], v[76:77], v[108:109]
	v_mov_b32_e32 v41, v95
	v_pk_fma_f32 v[44:45], v[44:45], v[110:111], v[46:47]
	v_mov_b32_e32 v46, v78
	v_mov_b32_e32 v47, v86
	v_pk_fma_f32 v[44:45], v[46:47], v[112:113], v[44:45] op_sel_hi:[1,0,1]
	v_mov_b32_e32 v86, v79
	v_pk_fma_f32 v[44:45], v[86:87], v[112:113], v[44:45] op_sel:[0,1,0]
	v_mov_b32_e32 v46, v80
	v_mov_b32_e32 v47, v88
	v_pk_fma_f32 v[44:45], v[46:47], v[102:103], v[44:45] op_sel_hi:[1,0,1]
	v_mov_b32_e32 v88, v81
	v_pk_fma_f32 v[44:45], v[88:89], v[102:103], v[44:45] op_sel:[0,1,0]
	v_mov_b32_e32 v46, v82
	v_mov_b32_e32 v47, v90
	v_mul_f32_e32 v42, v96, v102
	v_pk_fma_f32 v[44:45], v[46:47], v[114:115], v[44:45] op_sel_hi:[1,0,1]
	v_mov_b32_e32 v90, v83
	v_pk_add_f32 v[40:41], v[40:41], v[50:51]
	v_mov_b32_e32 v43, v104
	v_mul_f32_e32 v96, v97, v103
	v_pk_fma_f32 v[44:45], v[90:91], v[114:115], v[44:45] op_sel:[0,1,0]
	v_pk_mul_f32 v[48:49], v[106:107], v[114:115]
	v_pk_add_f32 v[40:41], v[42:43], v[40:41]
	v_mov_b32_e32 v97, v105
	v_pk_add_f32 v[26:27], v[26:27], v[44:45]
	v_mul_f32_e32 v44, v98, v114
	v_pk_add_f32 v[40:41], v[96:97], v[40:41]
	v_mov_b32_e32 v45, v48
	v_mul_f32_e32 v46, v99, v115
	v_pk_add_f32 v[40:41], v[44:45], v[40:41]
	v_mov_b32_e32 v47, v49
	v_pk_add_f32 v[40:41], v[46:47], v[40:41]
	v_and_b32_e32 v99, 0xffff0000, v8
	v_pk_add_f32 v[24:25], v[24:25], v[40:41]
	ds_read_b128 v[40:43], v39 offset:800
	ds_read_b128 v[44:47], v39 offset:816
	ds_read_b128 v[48:51], v39 offset:1568
	ds_read_b128 v[52:55], v39 offset:1584
	ds_read_b128 v[56:59], v39 offset:2336
	ds_read_b128 v[60:63], v39 offset:2352
	ds_read_b128 v[64:67], v39 offset:3104
	ds_read_b128 v[68:71], v39 offset:3120
	ds_read_b128 v[72:75], v39 offset:3872
	ds_read_b128 v[76:79], v39 offset:3888
	ds_read_b128 v[80:83], v39 offset:4640
	ds_read_b128 v[84:87], v39 offset:4656
	ds_read_b128 v[88:91], v39 offset:5408
	ds_read_b128 v[92:95], v39 offset:5424
	v_lshlrev_b32_e32 v96, 16, v8
	v_and_b32_e32 v98, 16, v8
	v_mov_b32_e32 v97, v99
	s_waitcnt lgkmcnt(13)
	v_pk_mov_b32 v[104:105], v[4:5], v[40:41] op_sel:[1,0]
	v_mov_b32_e32 v5, v41
	s_waitcnt lgkmcnt(3)
	v_mul_f32_e32 v8, v81, v99
	v_pk_mov_b32 v[98:99], v[98:99], v[96:97] op_sel:[1,0]
	v_pk_mul_f32 v[4:5], v[4:5], v[96:97]
	v_pk_fma_f32 v[80:81], v[80:81], v[96:97], v[8:9] op_sel_hi:[1,1,0]
	s_waitcnt lgkmcnt(1)
	v_mul_f32_e32 v8, v88, v96
	v_and_b32_e32 v101, 0xffff0000, v9
	v_lshlrev_b32_e32 v100, 16, v9
	v_pk_fma_f32 v[4:5], v[104:105], v[98:99], v[4:5]
	v_mov_b32_e32 v40, v6
	v_mov_b32_e32 v41, v42
	v_pk_fma_f32 v[88:89], v[88:89], v[96:97], v[8:9] op_sel_hi:[1,1,0]
	v_pk_fma_f32 v[4:5], v[40:41], v[100:101], v[4:5] op_sel_hi:[1,0,1]
	v_mov_b32_e32 v42, v7
	v_mul_f32_e32 v88, v82, v100
	v_mul_f32_e32 v8, v83, v101
	v_pk_mul_f32 v[82:83], v[90:91], v[100:101]
	v_and_b32_e32 v91, 0xffff0000, v10
	v_lshlrev_b32_e32 v90, 16, v10
	v_pk_fma_f32 v[4:5], v[42:43], v[100:101], v[4:5] op_sel:[0,1,0]
	v_mov_b32_e32 v6, v0
	v_mov_b32_e32 v7, v44
	v_pk_fma_f32 v[4:5], v[6:7], v[90:91], v[4:5] op_sel_hi:[1,0,1]
	v_mov_b32_e32 v44, v1
	v_and_b32_e32 v103, 0xffff0000, v11
	v_lshlrev_b32_e32 v102, 16, v11
	v_pk_fma_f32 v[0:1], v[44:45], v[90:91], v[4:5] op_sel:[0,1,0]
	v_mov_b32_e32 v4, v2
	v_mov_b32_e32 v5, v46
	v_pk_fma_f32 v[0:1], v[4:5], v[102:103], v[0:1] op_sel_hi:[1,0,1]
	v_mov_b32_e32 v46, v3
	v_pk_fma_f32 v[0:1], v[46:47], v[102:103], v[0:1] op_sel:[0,1,0]
	v_mov_b32_e32 v81, v82
	v_pk_add_f32 v[30:31], v[30:31], v[0:1]
	v_pk_mov_b32 v[0:1], v[48:49], v[56:57] op_sel:[1,0]
	v_mov_b32_e32 v49, v57
	v_pk_mul_f32 v[2:3], v[48:49], v[96:97]
	s_waitcnt lgkmcnt(0)
	v_pk_mul_f32 v[92:93], v[92:93], v[90:91]
	v_pk_fma_f32 v[0:1], v[0:1], v[98:99], v[2:3]
	v_mov_b32_e32 v2, v50
	v_mov_b32_e32 v3, v58
	v_pk_fma_f32 v[0:1], v[2:3], v[100:101], v[0:1] op_sel_hi:[1,0,1]
	v_mov_b32_e32 v58, v51
	v_pk_fma_f32 v[0:1], v[58:59], v[100:101], v[0:1] op_sel:[0,1,0]
	v_mov_b32_e32 v2, v52
	v_mov_b32_e32 v3, v60
	v_pk_fma_f32 v[0:1], v[2:3], v[90:91], v[0:1] op_sel_hi:[1,0,1]
	v_mov_b32_e32 v60, v53
	v_pk_fma_f32 v[0:1], v[60:61], v[90:91], v[0:1] op_sel:[0,1,0]
	v_mov_b32_e32 v2, v54
	v_mov_b32_e32 v3, v62
	v_pk_fma_f32 v[0:1], v[2:3], v[102:103], v[0:1] op_sel_hi:[1,0,1]
	v_mov_b32_e32 v62, v55
	v_pk_fma_f32 v[0:1], v[62:63], v[102:103], v[0:1] op_sel:[0,1,0]
	v_pk_add_f32 v[6:7], v[80:81], v[88:89]
	v_pk_add_f32 v[28:29], v[28:29], v[0:1]
	v_pk_mov_b32 v[0:1], v[64:65], v[72:73] op_sel:[1,0]
	v_mov_b32_e32 v65, v73
	v_pk_mul_f32 v[2:3], v[64:65], v[96:97]
	v_mov_b32_e32 v9, v83
	v_pk_fma_f32 v[0:1], v[0:1], v[98:99], v[2:3]
	v_mov_b32_e32 v2, v66
	v_mov_b32_e32 v3, v74
	v_pk_fma_f32 v[0:1], v[2:3], v[100:101], v[0:1] op_sel_hi:[1,0,1]
	v_mov_b32_e32 v74, v67
	v_pk_fma_f32 v[0:1], v[74:75], v[100:101], v[0:1] op_sel:[0,1,0]
	v_mov_b32_e32 v2, v68
	v_mov_b32_e32 v3, v76
	v_pk_fma_f32 v[0:1], v[2:3], v[90:91], v[0:1] op_sel_hi:[1,0,1]
	v_mov_b32_e32 v76, v69
	v_pk_fma_f32 v[0:1], v[76:77], v[90:91], v[0:1] op_sel:[0,1,0]
	v_mov_b32_e32 v2, v70
	v_mov_b32_e32 v3, v78
	v_mul_f32_e32 v10, v84, v90
	v_pk_fma_f32 v[0:1], v[2:3], v[102:103], v[0:1] op_sel_hi:[1,0,1]
	v_mov_b32_e32 v78, v71
	v_pk_add_f32 v[6:7], v[8:9], v[6:7]
	v_mov_b32_e32 v11, v92
	v_mul_f32_e32 v84, v85, v91
	v_pk_fma_f32 v[0:1], v[78:79], v[102:103], v[0:1] op_sel:[0,1,0]
	v_pk_mul_f32 v[4:5], v[94:95], v[102:103]
	v_pk_add_f32 v[6:7], v[10:11], v[6:7]
	v_mov_b32_e32 v85, v93
	v_pk_add_f32 v[26:27], v[26:27], v[0:1]
	v_mul_f32_e32 v0, v86, v102
	v_pk_add_f32 v[6:7], v[84:85], v[6:7]
	v_mov_b32_e32 v1, v4
	v_mul_f32_e32 v2, v87, v103
	v_pk_add_f32 v[0:1], v[0:1], v[6:7]
	v_mov_b32_e32 v3, v5
	v_pk_add_f32 v[0:1], v[2:3], v[0:1]
	v_add_u32_e32 v39, 64, v39
	v_pk_add_f32 v[24:25], v[24:25], v[0:1]
	s_cbranch_scc1 .LBB0_214

; __device__ __forceinline__ float bflo(unsigned w) { return __uint_as_float(w << 16); }
; __device__ __forceinline__ float bfhi(unsigned w) { return __uint_as_float(w & 0xffff0000u); }
; __device__ __forceinline__ void phase_attn_tail(KA a, LAS unsigned char* lds, int vcu, int G, int wave) {
;     ...
;         {
;             const int row = tid >> 5, dg = tid & 31;
;             const bf16* vp = KV + (size_t)k0 * 2048 + h * 256 + 128 + 4 * dg;
;             float o0 = 0.f, o1 = 0.f, o2 = 0.f, o3 = 0.f;
; #pragma unroll 8
;             for (int j = 0; j < nk; ++j) { const u32x2 vv = *(const u32x2*)(vp + (size_t)j * 2048); const float p = sc[row * 256 + j];
;                 o0 += p * bflo(vv.x); o1 += p * bfhi(vv.x); o2 += p * bflo(vv.y); o3 += p * bfhi(vv.y); }
;             *(f32x4*)(PART + ((size_t)(h * 33 + ck) * 16 + row) * 132 + 4 + 4 * dg) = (f32x4){o0, o1, o2, o3};
.Lpv_big:
	s_cmp_lt_u32 s20, 32
	s_cbranch_scc1 .Lpv_rem
	v_add_co_u32_e32 v188, vcc, 0xffff9000, v4
	s_mov_b64 s[18:19], 0x1000
	s_nop 0
	v_addc_co_u32_e32 v189, vcc, -1, v5, vcc
	global_load_dwordx2 v[64:65], v[188:189], off
	v_lshl_add_u64 v[188:189], v[188:189], 0, s[18:19]
	global_load_dwordx2 v[66:67], v[188:189], off
	v_lshl_add_u64 v[188:189], v[188:189], 0, s[18:19]
	global_load_dwordx2 v[68:69], v[188:189], off
	v_lshl_add_u64 v[188:189], v[188:189], 0, s[18:19]
	global_load_dwordx2 v[70:71], v[188:189], off
	v_lshl_add_u64 v[188:189], v[188:189], 0, s[18:19]
	global_load_dwordx2 v[72:73], v[188:189], off
	v_lshl_add_u64 v[188:189], v[188:189], 0, s[18:19]
	global_load_dwordx2 v[74:75], v[188:189], off
	v_lshl_add_u64 v[188:189], v[188:189], 0, s[18:19]
	global_load_dwordx2 v[76:77], v[188:189], off
	v_lshl_add_u64 v[188:189], v[188:189], 0, s[18:19]
	global_load_dwordx2 v[78:79], v[188:189], off
	v_lshl_add_u64 v[188:189], v[188:189], 0, s[18:19]
	global_load_dwordx2 v[80:81], v[188:189], off
	v_lshl_add_u64 v[188:189], v[188:189], 0, s[18:19]
	global_load_dwordx2 v[82:83], v[188:189], off
	v_lshl_add_u64 v[188:189], v[188:189], 0, s[18:19]
	global_load_dwordx2 v[84:85], v[188:189], off
	v_lshl_add_u64 v[188:189], v[188:189], 0, s[18:19]
	global_load_dwordx2 v[86:87], v[188:189], off
	v_lshl_add_u64 v[188:189], v[188:189], 0, s[18:19]
	global_load_dwordx2 v[88:89], v[188:189], off
	v_lshl_add_u64 v[188:189], v[188:189], 0, s[18:19]
	global_load_dwordx2 v[90:91], v[188:189], off
	v_lshl_add_u64 v[188:189], v[188:189], 0, s[18:19]
	global_load_dwordx2 v[92:93], v[188:189], off
	v_lshl_add_u64 v[188:189], v[188:189], 0, s[18:19]
	global_load_dwordx2 v[94:95], v[188:189], off
	v_lshl_add_u64 v[188:189], v[188:189], 0, s[18:19]
	global_load_dwordx2 v[96:97], v[188:189], off
	v_lshl_add_u64 v[188:189], v[188:189], 0, s[18:19]
	global_load_dwordx2 v[98:99], v[188:189], off
	v_lshl_add_u64 v[188:189], v[188:189], 0, s[18:19]
	global_load_dwordx2 v[100:101], v[188:189], off
	v_lshl_add_u64 v[188:189], v[188:189], 0, s[18:19]
	global_load_dwordx2 v[102:103], v[188:189], off
	v_lshl_add_u64 v[188:189], v[188:189], 0, s[18:19]
	global_load_dwordx2 v[104:105], v[188:189], off
	v_lshl_add_u64 v[188:189], v[188:189], 0, s[18:19]
	global_load_dwordx2 v[106:107], v[188:189], off
	v_lshl_add_u64 v[188:189], v[188:189], 0, s[18:19]
	global_load_dwordx2 v[108:109], v[188:189], off
	v_lshl_add_u64 v[188:189], v[188:189], 0, s[18:19]
	global_load_dwordx2 v[110:111], v[188:189], off
	v_lshl_add_u64 v[188:189], v[188:189], 0, s[18:19]
	global_load_dwordx2 v[112:113], v[188:189], off
	v_lshl_add_u64 v[188:189], v[188:189], 0, s[18:19]
	global_load_dwordx2 v[114:115], v[188:189], off
	v_lshl_add_u64 v[188:189], v[188:189], 0, s[18:19]
	global_load_dwordx2 v[116:117], v[188:189], off
	v_lshl_add_u64 v[188:189], v[188:189], 0, s[18:19]
	global_load_dwordx2 v[118:119], v[188:189], off
	v_lshl_add_u64 v[188:189], v[188:189], 0, s[18:19]
	global_load_dwordx2 v[120:121], v[188:189], off
	v_lshl_add_u64 v[188:189], v[188:189], 0, s[18:19]
	global_load_dwordx2 v[122:123], v[188:189], off
	v_lshl_add_u64 v[188:189], v[188:189], 0, s[18:19]
	global_load_dwordx2 v[124:125], v[188:189], off
	v_lshl_add_u64 v[188:189], v[188:189], 0, s[18:19]
	global_load_dwordx2 v[126:127], v[188:189], off
	ds_read_b128 v[156:159], v6
	ds_read_b128 v[160:163], v6 offset:16
	ds_read_b128 v[164:167], v6 offset:32
	ds_read_b128 v[168:171], v6 offset:48
	ds_read_b128 v[172:175], v6 offset:64
	ds_read_b128 v[176:179], v6 offset:80
	ds_read_b128 v[180:183], v6 offset:96
	ds_read_b128 v[184:187], v6 offset:112
	s_mov_b64 s[18:19], 0x20000
	s_add_i32 s20, s20, -32
	v_add_u32_e32 v6, 0x80, v6
	v_lshl_add_u64 v[4:5], v[4:5], 0, s[18:19]
	s_waitcnt lgkmcnt(0)
	s_waitcnt vmcnt(31)
	v_lshlrev_b32_e32 v190, 16, v64
	v_and_b32_e32 v191, 0xffff0000, v64
	v_lshlrev_b32_e32 v194, 16, v65
	v_and_b32_e32 v195, 0xffff0000, v65
	v_pk_fma_f32 v[0:1], v[156:157], v[190:191], v[0:1] op_sel_hi:[0,1,1]
	v_pk_fma_f32 v[2:3], v[156:157], v[194:195], v[2:3] op_sel_hi:[0,1,1]
	s_waitcnt vmcnt(30)
	v_lshlrev_b32_e32 v190, 16, v66
	v_and_b32_e32 v191, 0xffff0000, v66
	v_lshlrev_b32_e32 v194, 16, v67
	v_and_b32_e32 v195, 0xffff0000, v67
	v_pk_fma_f32 v[0:1], v[156:157], v[190:191], v[0:1] op_sel:[1,0,0]
	v_pk_fma_f32 v[2:3], v[156:157], v[194:195], v[2:3] op_sel:[1,0,0]
	s_waitcnt vmcnt(29)
	v_lshlrev_b32_e32 v190, 16, v68
	v_and_b32_e32 v191, 0xffff0000, v68
	v_lshlrev_b32_e32 v194, 16, v69
	v_and_b32_e32 v195, 0xffff0000, v69
	v_pk_fma_f32 v[0:1], v[158:159], v[190:191], v[0:1] op_sel_hi:[0,1,1]
	v_pk_fma_f32 v[2:3], v[158:159], v[194:195], v[2:3] op_sel_hi:[0,1,1]
	s_waitcnt vmcnt(28)
	v_lshlrev_b32_e32 v190, 16, v70
	v_and_b32_e32 v191, 0xffff0000, v70
	v_lshlrev_b32_e32 v194, 16, v71
	v_and_b32_e32 v195, 0xffff0000, v71
	v_pk_fma_f32 v[0:1], v[158:159], v[190:191], v[0:1] op_sel:[1,0,0]
	v_pk_fma_f32 v[2:3], v[158:159], v[194:195], v[2:3] op_sel:[1,0,0]
	s_waitcnt vmcnt(27)
	v_lshlrev_b32_e32 v190, 16, v72
	v_and_b32_e32 v191, 0xffff0000, v72
	v_lshlrev_b32_e32 v194, 16, v73
	v_and_b32_e32 v195, 0xffff0000, v73
	v_pk_fma_f32 v[0:1], v[160:161], v[190:191], v[0:1] op_sel_hi:[0,1,1]
	v_pk_fma_f32 v[2:3], v[160:161], v[194:195], v[2:3] op_sel_hi:[0,1,1]
	s_waitcnt vmcnt(26)
	v_lshlrev_b32_e32 v190, 16, v74
	v_and_b32_e32 v191, 0xffff0000, v74
	v_lshlrev_b32_e32 v194, 16, v75
	v_and_b32_e32 v195, 0xffff0000, v75
	v_pk_fma_f32 v[0:1], v[160:161], v[190:191], v[0:1] op_sel:[1,0,0]
	v_pk_fma_f32 v[2:3], v[160:161], v[194:195], v[2:3] op_sel:[1,0,0]
	s_waitcnt vmcnt(25)
; __device__ __forceinline__ float bflo(unsigned w) { return __uint_as_float(w << 16); }
; __device__ __forceinline__ float bfhi(unsigned w) { return __uint_as_float(w & 0xffff0000u); }
; __device__ __forceinline__ void phase_attn_tail(KA a, LAS unsigned char* lds, int vcu, int G, int wave) {
;     ...
;         {
;             const int row = tid >> 5, dg = tid & 31;
;             const bf16* vp = KV + (size_t)k0 * 2048 + h * 256 + 128 + 4 * dg;
;             float o0 = 0.f, o1 = 0.f, o2 = 0.f, o3 = 0.f;
; #pragma unroll 8
;             for (int j = 0; j < nk; ++j) { const u32x2 vv = *(const u32x2*)(vp + (size_t)j * 2048); const float p = sc[row * 256 + j];
;                 o0 += p * bflo(vv.x); o1 += p * bfhi(vv.x); o2 += p * bflo(vv.y); o3 += p * bfhi(vv.y); }
;             *(f32x4*)(PART + ((size_t)(h * 33 + ck) * 16 + row) * 132 + 4 + 4 * dg) = (f32x4){o0, o1, o2, o3};
	v_lshlrev_b32_e32 v190, 16, v76
	v_and_b32_e32 v191, 0xffff0000, v76
	v_lshlrev_b32_e32 v194, 16, v77
	v_and_b32_e32 v195, 0xffff0000, v77
	v_pk_fma_f32 v[0:1], v[162:163], v[190:191], v[0:1] op_sel_hi:[0,1,1]
	v_pk_fma_f32 v[2:3], v[162:163], v[194:195], v[2:3] op_sel_hi:[0,1,1]
	s_waitcnt vmcnt(24)
	v_lshlrev_b32_e32 v190, 16, v78
	v_and_b32_e32 v191, 0xffff0000, v78
	v_lshlrev_b32_e32 v194, 16, v79
	v_and_b32_e32 v195, 0xffff0000, v79
	v_pk_fma_f32 v[0:1], v[162:163], v[190:191], v[0:1] op_sel:[1,0,0]
	v_pk_fma_f32 v[2:3], v[162:163], v[194:195], v[2:3] op_sel:[1,0,0]
	s_waitcnt vmcnt(23)
	v_lshlrev_b32_e32 v190, 16, v80
	v_and_b32_e32 v191, 0xffff0000, v80
	v_lshlrev_b32_e32 v194, 16, v81
	v_and_b32_e32 v195, 0xffff0000, v81
	v_pk_fma_f32 v[0:1], v[164:165], v[190:191], v[0:1] op_sel_hi:[0,1,1]
	v_pk_fma_f32 v[2:3], v[164:165], v[194:195], v[2:3] op_sel_hi:[0,1,1]
	s_waitcnt vmcnt(22)
	v_lshlrev_b32_e32 v190, 16, v82
	v_and_b32_e32 v191, 0xffff0000, v82
	v_lshlrev_b32_e32 v194, 16, v83
	v_and_b32_e32 v195, 0xffff0000, v83
	v_pk_fma_f32 v[0:1], v[164:165], v[190:191], v[0:1] op_sel:[1,0,0]
	v_pk_fma_f32 v[2:3], v[164:165], v[194:195], v[2:3] op_sel:[1,0,0]
	s_waitcnt vmcnt(21)
	v_lshlrev_b32_e32 v190, 16, v84
	v_and_b32_e32 v191, 0xffff0000, v84
	v_lshlrev_b32_e32 v194, 16, v85
	v_and_b32_e32 v195, 0xffff0000, v85
	v_pk_fma_f32 v[0:1], v[166:167], v[190:191], v[0:1] op_sel_hi:[0,1,1]
	v_pk_fma_f32 v[2:3], v[166:167], v[194:195], v[2:3] op_sel_hi:[0,1,1]
	s_waitcnt vmcnt(20)
	v_lshlrev_b32_e32 v190, 16, v86
	v_and_b32_e32 v191, 0xffff0000, v86
	v_lshlrev_b32_e32 v194, 16, v87
	v_and_b32_e32 v195, 0xffff0000, v87
	v_pk_fma_f32 v[0:1], v[166:167], v[190:191], v[0:1] op_sel:[1,0,0]
	v_pk_fma_f32 v[2:3], v[166:167], v[194:195], v[2:3] op_sel:[1,0,0]
	s_waitcnt vmcnt(19)
	v_lshlrev_b32_e32 v190, 16, v88
	v_and_b32_e32 v191, 0xffff0000, v88
	v_lshlrev_b32_e32 v194, 16, v89
	v_and_b32_e32 v195, 0xffff0000, v89
	v_pk_fma_f32 v[0:1], v[168:169], v[190:191], v[0:1] op_sel_hi:[0,1,1]
	v_pk_fma_f32 v[2:3], v[168:169], v[194:195], v[2:3] op_sel_hi:[0,1,1]
	s_waitcnt vmcnt(18)
	v_lshlrev_b32_e32 v190, 16, v90
	v_and_b32_e32 v191, 0xffff0000, v90
	v_lshlrev_b32_e32 v194, 16, v91
	v_and_b32_e32 v195, 0xffff0000, v91
	v_pk_fma_f32 v[0:1], v[168:169], v[190:191], v[0:1] op_sel:[1,0,0]
	v_pk_fma_f32 v[2:3], v[168:169], v[194:195], v[2:3] op_sel:[1,0,0]
	s_waitcnt vmcnt(17)
	v_lshlrev_b32_e32 v190, 16, v92
	v_and_b32_e32 v191, 0xffff0000, v92
	v_lshlrev_b32_e32 v194, 16, v93
	v_and_b32_e32 v195, 0xffff0000, v93
	v_pk_fma_f32 v[0:1], v[170:171], v[190:191], v[0:1] op_sel_hi:[0,1,1]
	v_pk_fma_f32 v[2:3], v[170:171], v[194:195], v[2:3] op_sel_hi:[0,1,1]
	s_waitcnt vmcnt(16)
	v_lshlrev_b32_e32 v190, 16, v94
	v_and_b32_e32 v191, 0xffff0000, v94
	v_lshlrev_b32_e32 v194, 16, v95
	v_and_b32_e32 v195, 0xffff0000, v95
	v_pk_fma_f32 v[0:1], v[170:171], v[190:191], v[0:1] op_sel:[1,0,0]
	v_pk_fma_f32 v[2:3], v[170:171], v[194:195], v[2:3] op_sel:[1,0,0]
	s_waitcnt vmcnt(15)
	v_lshlrev_b32_e32 v190, 16, v96
	v_and_b32_e32 v191, 0xffff0000, v96
	v_lshlrev_b32_e32 v194, 16, v97
	v_and_b32_e32 v195, 0xffff0000, v97
	v_pk_fma_f32 v[0:1], v[172:173], v[190:191], v[0:1] op_sel_hi:[0,1,1]
	v_pk_fma_f32 v[2:3], v[172:173], v[194:195], v[2:3] op_sel_hi:[0,1,1]
	s_waitcnt vmcnt(14)
	v_lshlrev_b32_e32 v190, 16, v98
	v_and_b32_e32 v191, 0xffff0000, v98
	v_lshlrev_b32_e32 v194, 16, v99
	v_and_b32_e32 v195, 0xffff0000, v99
	v_pk_fma_f32 v[0:1], v[172:173], v[190:191], v[0:1] op_sel:[1,0,0]
	v_pk_fma_f32 v[2:3], v[172:173], v[194:195], v[2:3] op_sel:[1,0,0]
	s_waitcnt vmcnt(13)
	v_lshlrev_b32_e32 v190, 16, v100
	v_and_b32_e32 v191, 0xffff0000, v100
	v_lshlrev_b32_e32 v194, 16, v101
	v_and_b32_e32 v195, 0xffff0000, v101
	v_pk_fma_f32 v[0:1], v[174:175], v[190:191], v[0:1] op_sel_hi:[0,1,1]
	v_pk_fma_f32 v[2:3], v[174:175], v[194:195], v[2:3] op_sel_hi:[0,1,1]
	s_waitcnt vmcnt(12)
; __device__ __forceinline__ float bflo(unsigned w) { return __uint_as_float(w << 16); }
; __device__ __forceinline__ float bfhi(unsigned w) { return __uint_as_float(w & 0xffff0000u); }
; __device__ __forceinline__ void phase_attn_tail(KA a, LAS unsigned char* lds, int vcu, int G, int wave) {
;     ...
;         {
;             const int row = tid >> 5, dg = tid & 31;
;             const bf16* vp = KV + (size_t)k0 * 2048 + h * 256 + 128 + 4 * dg;
;             float o0 = 0.f, o1 = 0.f, o2 = 0.f, o3 = 0.f;
; #pragma unroll 8
;             for (int j = 0; j < nk; ++j) { const u32x2 vv = *(const u32x2*)(vp + (size_t)j * 2048); const float p = sc[row * 256 + j];
;                 o0 += p * bflo(vv.x); o1 += p * bfhi(vv.x); o2 += p * bflo(vv.y); o3 += p * bfhi(vv.y); }
;             *(f32x4*)(PART + ((size_t)(h * 33 + ck) * 16 + row) * 132 + 4 + 4 * dg) = (f32x4){o0, o1, o2, o3};
	v_lshlrev_b32_e32 v190, 16, v102
	v_and_b32_e32 v191, 0xffff0000, v102
	v_lshlrev_b32_e32 v194, 16, v103
	v_and_b32_e32 v195, 0xffff0000, v103
	v_pk_fma_f32 v[0:1], v[174:175], v[190:191], v[0:1] op_sel:[1,0,0]
	v_pk_fma_f32 v[2:3], v[174:175], v[194:195], v[2:3] op_sel:[1,0,0]
	s_waitcnt vmcnt(11)
	v_lshlrev_b32_e32 v190, 16, v104
	v_and_b32_e32 v191, 0xffff0000, v104
	v_lshlrev_b32_e32 v194, 16, v105
	v_and_b32_e32 v195, 0xffff0000, v105
	v_pk_fma_f32 v[0:1], v[176:177], v[190:191], v[0:1] op_sel_hi:[0,1,1]
	v_pk_fma_f32 v[2:3], v[176:177], v[194:195], v[2:3] op_sel_hi:[0,1,1]
	s_waitcnt vmcnt(10)
	v_lshlrev_b32_e32 v190, 16, v106
	v_and_b32_e32 v191, 0xffff0000, v106
	v_lshlrev_b32_e32 v194, 16, v107
	v_and_b32_e32 v195, 0xffff0000, v107
	v_pk_fma_f32 v[0:1], v[176:177], v[190:191], v[0:1] op_sel:[1,0,0]
	v_pk_fma_f32 v[2:3], v[176:177], v[194:195], v[2:3] op_sel:[1,0,0]
	s_waitcnt vmcnt(9)
	v_lshlrev_b32_e32 v190, 16, v108
	v_and_b32_e32 v191, 0xffff0000, v108
	v_lshlrev_b32_e32 v194, 16, v109
	v_and_b32_e32 v195, 0xffff0000, v109
	v_pk_fma_f32 v[0:1], v[178:179], v[190:191], v[0:1] op_sel_hi:[0,1,1]
	v_pk_fma_f32 v[2:3], v[178:179], v[194:195], v[2:3] op_sel_hi:[0,1,1]
	s_waitcnt vmcnt(8)
	v_lshlrev_b32_e32 v190, 16, v110
	v_and_b32_e32 v191, 0xffff0000, v110
	v_lshlrev_b32_e32 v194, 16, v111
	v_and_b32_e32 v195, 0xffff0000, v111
	v_pk_fma_f32 v[0:1], v[178:179], v[190:191], v[0:1] op_sel:[1,0,0]
	v_pk_fma_f32 v[2:3], v[178:179], v[194:195], v[2:3] op_sel:[1,0,0]
	s_waitcnt vmcnt(7)
	v_lshlrev_b32_e32 v190, 16, v112
	v_and_b32_e32 v191, 0xffff0000, v112
	v_lshlrev_b32_e32 v194, 16, v113
	v_and_b32_e32 v195, 0xffff0000, v113
	v_pk_fma_f32 v[0:1], v[180:181], v[190:191], v[0:1] op_sel_hi:[0,1,1]
	v_pk_fma_f32 v[2:3], v[180:181], v[194:195], v[2:3] op_sel_hi:[0,1,1]
	s_waitcnt vmcnt(6)
	v_lshlrev_b32_e32 v190, 16, v114
	v_and_b32_e32 v191, 0xffff0000, v114
	v_lshlrev_b32_e32 v194, 16, v115
	v_and_b32_e32 v195, 0xffff0000, v115
	v_pk_fma_f32 v[0:1], v[180:181], v[190:191], v[0:1] op_sel:[1,0,0]
	v_pk_fma_f32 v[2:3], v[180:181], v[194:195], v[2:3] op_sel:[1,0,0]
	s_waitcnt vmcnt(5)
	v_lshlrev_b32_e32 v190, 16, v116
	v_and_b32_e32 v191, 0xffff0000, v116
	v_lshlrev_b32_e32 v194, 16, v117
	v_and_b32_e32 v195, 0xffff0000, v117
	v_pk_fma_f32 v[0:1], v[182:183], v[190:191], v[0:1] op_sel_hi:[0,1,1]
	v_pk_fma_f32 v[2:3], v[182:183], v[194:195], v[2:3] op_sel_hi:[0,1,1]
	s_waitcnt vmcnt(4)
	v_lshlrev_b32_e32 v190, 16, v118
	v_and_b32_e32 v191, 0xffff0000, v118
	v_lshlrev_b32_e32 v194, 16, v119
	v_and_b32_e32 v195, 0xffff0000, v119
	v_pk_fma_f32 v[0:1], v[182:183], v[190:191], v[0:1] op_sel:[1,0,0]
	v_pk_fma_f32 v[2:3], v[182:183], v[194:195], v[2:3] op_sel:[1,0,0]
	s_waitcnt vmcnt(3)
	v_lshlrev_b32_e32 v190, 16, v120
	v_and_b32_e32 v191, 0xffff0000, v120
	v_lshlrev_b32_e32 v194, 16, v121
	v_and_b32_e32 v195, 0xffff0000, v121
	v_pk_fma_f32 v[0:1], v[184:185], v[190:191], v[0:1] op_sel_hi:[0,1,1]
	v_pk_fma_f32 v[2:3], v[184:185], v[194:195], v[2:3] op_sel_hi:[0,1,1]
	s_waitcnt vmcnt(2)
	v_lshlrev_b32_e32 v190, 16, v122
	v_and_b32_e32 v191, 0xffff0000, v122
	v_lshlrev_b32_e32 v194, 16, v123
	v_and_b32_e32 v195, 0xffff0000, v123
	v_pk_fma_f32 v[0:1], v[184:185], v[190:191], v[0:1] op_sel:[1,0,0]
	v_pk_fma_f32 v[2:3], v[184:185], v[194:195], v[2:3] op_sel:[1,0,0]
	s_waitcnt vmcnt(1)
	v_lshlrev_b32_e32 v190, 16, v124
	v_and_b32_e32 v191, 0xffff0000, v124
	v_lshlrev_b32_e32 v194, 16, v125
	v_and_b32_e32 v195, 0xffff0000, v125
	v_pk_fma_f32 v[0:1], v[186:187], v[190:191], v[0:1] op_sel_hi:[0,1,1]
	v_pk_fma_f32 v[2:3], v[186:187], v[194:195], v[2:3] op_sel_hi:[0,1,1]
	s_waitcnt vmcnt(0)
	v_lshlrev_b32_e32 v190, 16, v126
	v_and_b32_e32 v191, 0xffff0000, v126
	v_lshlrev_b32_e32 v194, 16, v127
	v_and_b32_e32 v195, 0xffff0000, v127
	v_pk_fma_f32 v[0:1], v[186:187], v[190:191], v[0:1] op_sel:[1,0,0]
	v_pk_fma_f32 v[2:3], v[186:187], v[194:195], v[2:3] op_sel:[1,0,0]
	s_branch .Lpv_big
.Lpv_rem:
	s_cmp_eq_u32 s20, 0
	s_cbranch_scc1 .Lpv_done

; __device__ __forceinline__ void phase_attn_tail(KA a, LAS unsigned char* lds, int vcu, int G, int wave) {
;     ...
;             *(f32x4*)(PART + ((size_t)(h * 33 + ck) * 16 + row) * 132 + 4 + 4 * dg) = (f32x4){o0, o1, o2, o3};
;         }
;         __syncthreads();
;     }
.Lpv_done:
	v_lshl_add_u64 v[4:5], s[54:55], 0, v[16:17]
	s_movk_i32 s0, 0x210
	v_mad_u64_u32 v[6:7], s[18:19], v4, s0, v[18:19]
	s_add_i32 s11, s11, s15
	v_mad_i32_i24 v7, v5, s0, v7
	s_cmpk_gt_i32 s11, 0x107
	global_store_dwordx4 v[6:7], v[0:3], off offset:16
	s_barrier
	s_cbranch_scc0 .LBB0_202
	v_readlane_b32 s11, v255, 7

; __device__ __forceinline__ float bf2f(unsigned short u) { return __uint_as_float((unsigned)u << 16); }
; __device__ __forceinline__ float bflo(unsigned w) { return __uint_as_float(w << 16); }
; __device__ __forceinline__ float bfhi(unsigned w) { return __uint_as_float(w & 0xffff0000u); }
; __device__ __forceinline__ void sconv8(const bf16* urow, float w0, float w1, float w2, float b, int t0, float (&o)[8]) {
;     const u32x4 c = *(const u32x4*)(urow + t0);
;     const float um = t0 > 0 ? bf2f(urow[t0 - 1]) : 0.f, up = t0 + 8 < T_ ? bf2f(urow[t0 + 8]) : 0.f;
;     const float u[10] = {um, bflo(c.x), bfhi(c.x), bflo(c.y), bfhi(c.y), bflo(c.z), bfhi(c.z), bflo(c.w), bfhi(c.w), up};
; __device__ __forceinline__ void phase_fft(KA a, int l, LAS unsigned char* lds, int vcu, int G, int wave) {
;     ...
;             for (int i = 0; i < 3; ++i) { const int chk = tid + 512 * i, t0 = chk * 8;
;                 if (t0 < T_) {
;                     float zz0[8], zz1[8];
;                     sconv8(uv0, wv00, wv01, wv02, bv0, t0, zz0); { float tmp[8]; sconv8(ua0, wa00, wa01, wa02, ba0, t0, tmp);
; #pragma unroll
;                         for (int e = 0; e < 8; ++e) zz0[e] *= tmp[e]; }
;                     sconv8(uv1, wv10, wv11, wv12, bv1, t0, zz1); { float tmp[8]; sconv8(ua1, wa10, wa11, wa12, ba1, t0, tmp);
; #pragma unroll
;                         for (int e = 0; e < 8; ++e) zz1[e] *= tmp[e]; }
.LBB0_269:
	s_andn2_saveexec_b64 s[54:55], s[22:23]
	s_cbranch_execz .LBB0_264
	v_mov_b32_e32 v132, 0
	v_mov_b32_e32 v133, 0
	v_mov_b32_e32 v134, 0
	v_mov_b32_e32 v135, 0
	v_mov_b32_e32 v136, 0
	v_mov_b32_e32 v137, 0
	v_mov_b32_e32 v138, 0
	v_mov_b32_e32 v139, 0
	v_ashrrev_i32_e32 v105, 31, v104
	v_lshl_add_u64 v[0:1], v[104:105], 1, s[58:59]
	global_load_dwordx4 v[4:7], v[0:1], off
	v_cmp_lt_i32_e32 vcc, 0, v104
	v_mov_b32_e32 v97, 0
	v_mov_b32_e32 v115, 0
	s_and_saveexec_b64 s[22:23], vcc
	s_cbranch_execz .LBB0_272
	v_mov_b32_e32 v148, v104
	v_lshl_add_u64 v[2:3], v[148:149], 1, s[58:59]
	global_load_ushort v132, v[2:3], off offset:-2
.LBB0_272:
	s_or_b64 exec, exec, s[22:23]
	s_movk_i32 s0, 0x2008
	v_cmp_gt_i32_e64 s[42:43], s0, v104
	s_and_saveexec_b64 s[22:23], s[42:43]
	s_cbranch_execz .LBB0_274
	global_load_ushort v133, v[0:1], off offset:16
.LBB0_274:
	s_or_b64 exec, exec, s[22:23]
	v_lshl_add_u64 v[8:9], v[104:105], 1, s[60:61]
	global_load_dwordx4 v[0:3], v[8:9], off
	v_mov_b32_e32 v18, 0
	v_mov_b32_e32 v114, 0
	s_and_saveexec_b64 s[22:23], vcc
	s_cbranch_execz .LBB0_276
	v_mov_b32_e32 v148, v104
	v_lshl_add_u64 v[10:11], v[148:149], 1, s[60:61]
	global_load_ushort v134, v[10:11], off offset:-2
.LBB0_276:
	s_or_b64 exec, exec, s[22:23]
	s_and_saveexec_b64 s[22:23], s[42:43]
	s_cbranch_execz .LBB0_278
	global_load_ushort v135, v[8:9], off offset:16
.LBB0_278:
	s_or_b64 exec, exec, s[22:23]
	v_lshl_add_u64 v[8:9], v[104:105], 1, s[62:63]
	global_load_dwordx4 v[12:15], v[8:9], off
	v_mov_b32_e32 v116, 0
	v_mov_b32_e32 v117, 0
	s_and_saveexec_b64 s[22:23], vcc
	s_cbranch_execz .LBB0_280
	v_mov_b32_e32 v148, v104
	v_lshl_add_u64 v[10:11], v[148:149], 1, s[62:63]
	global_load_ushort v136, v[10:11], off offset:-2
.LBB0_280:
	s_or_b64 exec, exec, s[22:23]
	s_and_saveexec_b64 s[22:23], s[42:43]
	s_cbranch_execz .LBB0_282
	global_load_ushort v137, v[8:9], off offset:16
.LBB0_282:
	s_or_b64 exec, exec, s[22:23]
	v_lshl_add_u64 v[16:17], v[104:105], 1, s[56:57]
	global_load_dwordx4 v[8:11], v[16:17], off
	v_mov_b32_e32 v19, 0
	v_mov_b32_e32 v105, 0
	s_and_saveexec_b64 s[22:23], vcc
	s_cbranch_execz .LBB0_284
	v_mov_b32_e32 v105, v149
	v_lshl_add_u64 v[118:119], v[104:105], 1, s[56:57]
	global_load_ushort v138, v[118:119], off offset:-2
.LBB0_284:
	s_or_b64 exec, exec, s[22:23]
	s_and_saveexec_b64 s[22:23], s[42:43]
	s_cbranch_execz .LBB0_286
	global_load_ushort v139, v[16:17], off offset:16
; #define LAS __attribute__((address_space(3)))
; __device__ __forceinline__ float bf2f(unsigned short u) { return __uint_as_float((unsigned)u << 16); }
; __device__ __forceinline__ float bflo(unsigned w) { return __uint_as_float(w << 16); }
; __device__ __forceinline__ float bfhi(unsigned w) { return __uint_as_float(w & 0xffff0000u); }
; __device__ __forceinline__ void sconv8(const bf16* urow, float w0, float w1, float w2, float b, int t0, float (&o)[8]) {
;     const u32x4 c = *(const u32x4*)(urow + t0);
;     const float um = t0 > 0 ? bf2f(urow[t0 - 1]) : 0.f, up = t0 + 8 < T_ ? bf2f(urow[t0 + 8]) : 0.f;
;     const float u[10] = {um, bflo(c.x), bfhi(c.x), bflo(c.y), bfhi(c.y), bflo(c.z), bfhi(c.z), bflo(c.w), bfhi(c.w), up};
; #pragma unroll
;     for (int e = 0; e < 8; ++e) o[e] = u[e] * w0 + u[e + 1] * w1 + u[e + 2] * w2 + b;
; }
; __device__ __forceinline__ void phase_fft(KA a, int l, LAS unsigned char* lds, int vcu, int G, int wave) {
;     ...
;             for (int i = 0; i < 3; ++i) { const int chk = tid + 512 * i, t0 = chk * 8;
;                 if (t0 < T_) {
;                     float zz0[8], zz1[8];
;                     sconv8(uv0, wv00, wv01, wv02, bv0, t0, zz0); { float tmp[8]; sconv8(ua0, wa00, wa01, wa02, ba0, t0, tmp);
; #pragma unroll
;                         for (int e = 0; e < 8; ++e) zz0[e] *= tmp[e]; }
;                     sconv8(uv1, wv10, wv11, wv12, bv1, t0, zz1); { float tmp[8]; sconv8(ua1, wa10, wa11, wa12, ba1, t0, tmp);
; #pragma unroll
;                         for (int e = 0; e < 8; ++e) zz1[e] *= tmp[e]; }
; #pragma unroll
;                     for (int e = 0; e < 8; e += 2) *(LAS f32x4*)(x + fsw(t0 + e)) = (f32x4){zz0[e], zz1[e], zz0[e + 1], zz1[e + 1]};
; #pragma unroll
;                     for (int e = 0; e < 8; ++e) { const int t = t0 + e; if (t <= 30) { zb[t] = zz0[e]; zb[64 + t] = zz1[e]; } if (t >= LB) { zb[32 + t - LB] = zz0[e]; zb[96 + t - LB] = zz1[e]; } }
.LBB0_286:
	s_or_b64 exec, exec, s[22:23]
	s_waitcnt vmcnt(0)
	v_lshlrev_b32_e32 v115, 16, v132
	v_lshlrev_b32_e32 v97, 16, v133
	v_lshlrev_b32_e32 v114, 16, v134
	v_lshlrev_b32_e32 v18, 16, v135
	v_lshlrev_b32_e32 v117, 16, v136
	v_lshlrev_b32_e32 v116, 16, v137
	v_lshlrev_b32_e32 v105, 16, v138
	v_lshlrev_b32_e32 v19, 16, v139
	v_lshlrev_b32_e32 v16, 16, v12
	v_mul_f32_e32 v117, v113, v117
	v_and_b32_e32 v12, 0xffff0000, v12
	v_fmac_f32_e32 v117, v87, v16
	v_fmac_f32_e32 v117, v89, v12
	v_lshlrev_b32_e32 v17, 16, v13
	v_add_f32_e32 v122, v91, v117
	v_mul_f32_e32 v117, v87, v12
	v_and_b32_e32 v13, 0xffff0000, v13
	v_fmac_f32_e32 v117, v113, v16
	v_mul_f32_e32 v16, v87, v17
	v_fmac_f32_e32 v16, v113, v12
	v_mul_f32_e32 v12, v87, v13
	v_lshlrev_b32_e32 v118, 16, v14
	v_fmac_f32_e32 v12, v113, v17
	v_fmac_f32_e32 v12, v89, v118
	v_add_f32_e32 v125, v91, v12
	v_mul_f32_e32 v12, v87, v118
	v_and_b32_e32 v14, 0xffff0000, v14
	v_fmac_f32_e32 v12, v113, v13
	v_fmac_f32_e32 v12, v89, v14
	v_add_f32_e32 v126, v91, v12
	v_mul_f32_e32 v12, v87, v14
	v_lshlrev_b32_e32 v119, 16, v15
	v_fmac_f32_e32 v12, v113, v118
	v_fmac_f32_e32 v12, v89, v119
	v_add_f32_e32 v127, v91, v12
	v_mul_f32_e32 v12, v87, v119
	v_and_b32_e32 v15, 0xffff0000, v15
	v_fmac_f32_e32 v12, v113, v14
	v_fmac_f32_e32 v12, v89, v15
	v_add_f32_e32 v128, v91, v12
	v_mul_f32_e32 v12, v87, v15
	v_fmac_f32_e32 v12, v113, v119
	v_fmac_f32_e32 v12, v89, v116
	v_add_f32_e32 v129, v91, v12
	v_lshlrev_b32_e32 v12, 16, v4
	v_and_b32_e32 v4, 0xffff0000, v4
	v_fmac_f32_e32 v117, v89, v17
	v_mul_f32_e32 v17, v86, v4
	v_fmac_f32_e32 v16, v89, v13
	v_lshlrev_b32_e32 v13, 16, v5
	v_fmac_f32_e32 v17, v112, v12
	v_add_f32_e32 v124, v91, v16
	v_mul_f32_e32 v16, v112, v115
	v_fmac_f32_e32 v17, v88, v13
	v_fmac_f32_e32 v16, v86, v12
	v_add_f32_e32 v12, v90, v17
	v_mul_f32_e32 v17, v86, v13
	v_and_b32_e32 v5, 0xffff0000, v5
	v_fmac_f32_e32 v17, v112, v4
	v_fmac_f32_e32 v17, v88, v5
	v_fmac_f32_e32 v16, v88, v4
	v_add_f32_e32 v4, v90, v17
	v_mul_f32_e32 v17, v86, v5
	v_lshlrev_b32_e32 v14, 16, v6
	v_fmac_f32_e32 v17, v112, v13
	v_fmac_f32_e32 v17, v88, v14
	v_add_f32_e32 v13, v90, v17
	v_mul_f32_e32 v17, v86, v14
	v_and_b32_e32 v6, 0xffff0000, v6
	v_fmac_f32_e32 v17, v112, v5
	v_fmac_f32_e32 v17, v88, v6
	v_lshlrev_b32_e32 v15, 16, v7
	v_add_f32_e32 v5, v90, v17
	v_mul_f32_e32 v17, v86, v6
	v_and_b32_e32 v7, 0xffff0000, v7
	v_fmac_f32_e32 v17, v112, v14
	v_mul_f32_e32 v14, v86, v15
	v_fmac_f32_e32 v14, v112, v6
	v_mul_f32_e32 v6, v86, v7
	v_fmac_f32_e32 v6, v112, v15
	v_fmac_f32_e32 v6, v88, v97
	v_fmac_f32_e32 v14, v88, v7
	v_add_f32_e32 v7, v90, v6
	v_lshlrev_b32_e32 v6, 16, v0
	v_and_b32_e32 v0, 0xffff0000, v0
	v_mul_f32_e32 v116, v94, v0
	v_add_f32_e32 v115, v90, v14
	v_lshlrev_b32_e32 v14, 16, v1
	v_fmac_f32_e32 v116, v92, v6
	v_mul_f32_e32 v114, v92, v114
	v_fmac_f32_e32 v116, v96, v14
	v_fmac_f32_e32 v114, v94, v6
	v_add_f32_e32 v6, v98, v116
	v_mul_f32_e32 v116, v94, v14
	v_and_b32_e32 v1, 0xffff0000, v1
	v_fmac_f32_e32 v116, v92, v0
	v_fmac_f32_e32 v116, v96, v1
	v_fmac_f32_e32 v114, v96, v0
	v_add_f32_e32 v0, v98, v116
	v_mul_f32_e32 v116, v94, v1
	v_fmac_f32_e32 v17, v88, v15
	v_lshlrev_b32_e32 v15, 16, v2
	v_fmac_f32_e32 v116, v92, v14
	v_fmac_f32_e32 v116, v96, v15
	v_add_f32_e32 v14, v98, v116
	v_mul_f32_e32 v116, v94, v15
	v_and_b32_e32 v2, 0xffff0000, v2
	v_fmac_f32_e32 v116, v92, v1
	v_fmac_f32_e32 v116, v96, v2
	v_add_f32_e32 v1, v98, v116
	v_mul_f32_e32 v116, v94, v2
	v_lshlrev_b32_e32 v97, 16, v3
	v_fmac_f32_e32 v116, v92, v15
	v_fmac_f32_e32 v116, v96, v97
	v_add_f32_e32 v15, v98, v116
	v_mul_f32_e32 v116, v94, v97
	v_and_b32_e32 v3, 0xffff0000, v3
	v_fmac_f32_e32 v116, v92, v2
	v_fmac_f32_e32 v116, v96, v3
	v_mul_f32_e32 v3, v94, v3
	v_add_f32_e32 v16, v90, v16
	v_add_f32_e32 v114, v98, v114
	v_add_f32_e32 v2, v98, v116
	v_fmac_f32_e32 v3, v92, v97
	s_waitcnt vmcnt(0)
	v_and_b32_e32 v118, 0xffff0000, v8
	v_fmac_f32_e32 v3, v96, v18
	v_mul_f32_e32 v16, v16, v114
	v_mul_f32_e32 v18, v12, v6
	v_mul_f32_e32 v12, v4, v0
	v_mul_f32_e32 v0, v115, v2
	v_lshlrev_b32_e32 v115, 16, v8
	v_mov_b32_e32 v114, v118
	v_lshlrev_b32_e32 v119, 16, v9
	v_pk_mul_f32 v[120:121], v[102:103], v[114:115]
	v_and_b32_e32 v114, 0xffff0000, v9
	v_mul_f32_e32 v4, v5, v1
	v_fma_f32 v1, v93, v105, v121
	v_mov_b32_e32 v8, v114
	v_mov_b32_e32 v9, v119
	v_add_f32_e32 v3, v98, v3
	v_add_f32_e32 v1, v120, v1
	v_pk_mul_f32 v[120:121], v[100:101], v[118:119]
	v_pk_mul_f32 v[8:9], v[102:103], v[8:9]
	v_mul_f32_e32 v2, v7, v3
	v_fma_f32 v3, v93, v115, v120
	v_lshlrev_b32_e32 v115, 16, v10
	v_fma_f32 v5, v93, v118, v9
	v_add_f32_e32 v5, v8, v5
	v_pk_mul_f32 v[8:9], v[100:101], v[114:115]
	v_and_b32_e32 v116, 0xffff0000, v11
	v_fma_f32 v7, v93, v119, v8
	v_and_b32_e32 v8, 0xffff0000, v10
	v_add_f32_e32 v7, v9, v7
	v_lshlrev_b32_e32 v9, 16, v11
	v_mov_b32_e32 v10, v8
	v_mov_b32_e32 v11, v115
	v_pk_mul_f32 v[10:11], v[102:103], v[10:11]
	v_add_f32_e32 v123, v91, v117
	v_fma_f32 v11, v93, v114, v11
	v_add_f32_e32 v10, v10, v11
	v_add_f32_e32 v97, v99, v10
	v_pk_mul_f32 v[10:11], v[100:101], v[8:9]
	v_mov_b32_e32 v117, v9
	v_fma_f32 v10, v93, v115, v10
	v_add_f32_e32 v10, v11, v10
	v_add_f32_e32 v105, v99, v10
	v_pk_mul_f32 v[10:11], v[102:103], v[116:117]
	v_mov_b32_e32 v117, v19
	v_fma_f32 v8, v93, v8, v11
	v_add_f32_e32 v8, v10, v8
	v_add_f32_e32 v17, v90, v17
	v_add_f32_e32 v1, v99, v1
	v_add_f32_e32 v3, v121, v3
	v_add_f32_e32 v8, v99, v8
	v_pk_mul_f32 v[10:11], v[100:101], v[116:117]
	v_mul_f32_e32 v6, v17, v15
	v_add_f32_e32 v3, v99, v3
	v_fma_f32 v9, v93, v9, v10
	v_mul_f32_e32 v17, v122, v1
	v_mul_f32_e32 v1, v128, v8
	v_xor_b32_e32 v8, v104, v108
	v_add_f32_e32 v9, v9, v11
	v_mul_f32_e32 v19, v123, v3
	v_lshl_add_u32 v8, v8, 3, 0
	v_add_u32_e32 v11, 2, v104
	v_add_f32_e32 v5, v99, v5
	v_add_f32_e32 v7, v99, v7
	ds_write_b128 v8, v[16:19]
	v_xor_b32_e32 v8, v11, v108
	v_mul_f32_e32 v14, v13, v14
	v_mul_f32_e32 v13, v124, v5
	v_mul_f32_e32 v15, v125, v7
	v_lshl_add_u32 v8, v8, 3, 0
	v_add_u32_e32 v10, 4, v104
	v_add_f32_e32 v9, v99, v9
	ds_write_b128 v8, v[12:15]
	v_xor_b32_e32 v8, v10, v108
	v_mul_f32_e32 v5, v126, v97
	v_mul_f32_e32 v7, v127, v105
	v_mul_f32_e32 v3, v129, v9
	v_lshl_add_u32 v8, v8, 3, 0
	v_add_u32_e32 v9, 6, v104
	ds_write_b128 v8, v[4:7]
	v_xor_b32_e32 v8, v9, v108
	v_lshl_add_u32 v8, v8, 3, 0
	ds_write_b128 v8, v[0:3]
	v_cmp_gt_i32_e32 vcc, 31, v104
	v_add_u32_e32 v8, s7, v95
	s_and_saveexec_b64 s[22:23], vcc
	s_cbranch_execz .LBB0_288
	v_add_u32_e32 v97, 0x20000, v8
	v_add_u32_e32 v105, 0x20100, v8
	ds_write_b32 v97, v16
	ds_write_b32 v105, v17

; #define LAS __attribute__((address_space(3)))
; __device__ __forceinline__ unsigned pk2(float lo, float hi) { return pg8::cvt_pk_bf16(lo, hi); }
; __device__ __forceinline__ float bf2f(unsigned short u) { return __uint_as_float((unsigned)u << 16); }
; __device__ __forceinline__ float bflo(unsigned w) { return __uint_as_float(w << 16); }
; __device__ __forceinline__ float bfhi(unsigned w) { return __uint_as_float(w & 0xffff0000u); }
; __device__ __forceinline__ void sconv8(const bf16* urow, float w0, float w1, float w2, float b, int t0, float (&o)[8]) {
;     const u32x4 c = *(const u32x4*)(urow + t0);
;     const float um = t0 > 0 ? bf2f(urow[t0 - 1]) : 0.f, up = t0 + 8 < T_ ? bf2f(urow[t0 + 8]) : 0.f;
;     const float u[10] = {um, bflo(c.x), bfhi(c.x), bflo(c.y), bfhi(c.y), bflo(c.z), bfhi(c.z), bflo(c.w), bfhi(c.w), up};
; #pragma unroll
;     for (int e = 0; e < 8; ++e) o[e] = u[e] * w0 + u[e + 1] * w1 + u[e + 2] * w2 + b;
; }
; __device__ __forceinline__ void phase_fft(KA a, int l, LAS unsigned char* lds, int vcu, int G, int wave) {
;     ...
;             for (int i = 0; i < 3; ++i) { const int t0 = 8 * (tid + 512 * i);
;                 if (t0 < T_) {
;                     float g0[8], g1[8]; sconv8(u00, wx00, wx01, wx02, bx0, t0, g0); sconv8(u01, wx10, wx11, wx12, bx1, t0, g1);
;                     float y0[8], y1[8];
; #pragma unroll
;                     for (int e = 0; e < 8; e += 2) { const f32x4 yy = *(const LAS f32x4*)(x + fsw(t0 + e)); y0[e] = yy.x; y1[e] = yy.y; y0[e + 1] = yy.z; y1[e + 1] = yy.w; }
;                     const float sc = 1.0f / (float)FN;
;                     u32x4 w0, w1;
;                     w0.x = pk2(y0[0] * sc * g0[0], y0[1] * sc * g0[1]); w0.y = pk2(y0[2] * sc * g0[2], y0[3] * sc * g0[3]); w0.z = pk2(y0[4] * sc * g0[4], y0[5] * sc * g0[5]); w0.w = pk2(y0[6] * sc * g0[6], y0[7] * sc * g0[7]);
;                     w1.x = pk2(y1[0] * sc * g1[0], y1[1] * sc * g1[1]); w1.y = pk2(y1[2] * sc * g1[2], y1[3] * sc * g1[3]); w1.z = pk2(y1[4] * sc * g1[4], y1[5] * sc * g1[5]); w1.w = pk2(y1[6] * sc * g1[6], y1[7] * sc * g1[7]);
;                     *(u32x4*)(YT + (size_t)c0 * TP + t0) = w0; *(u32x4*)(YT + (size_t)c1 * TP + t0) = w1;
.LBB0_354:
	s_or_b64 exec, exec, s[22:23]
	s_waitcnt vmcnt(0)
	v_lshlrev_b32_e32 v22, 16, v140
	v_lshlrev_b32_e32 v11, 16, v141
	v_lshlrev_b32_e32 v13, 16, v142
	v_lshlrev_b32_e32 v23, 16, v143
	v_lshlrev_b32_e32 v24, 16, v4
	v_mul_f32_e32 v22, v8, v22
	v_and_b32_e32 v4, 0xffff0000, v4
	v_fmac_f32_e32 v22, v10, v24
	v_fmac_f32_e32 v22, v12, v4
	v_add_f32_e32 v30, v14, v22
	v_mul_f32_e32 v22, v10, v4
	v_lshlrev_b32_e32 v25, 16, v5
	v_fmac_f32_e32 v22, v8, v24
	v_fmac_f32_e32 v22, v12, v25
	v_and_b32_e32 v5, 0xffff0000, v5
	v_add_f32_e32 v31, v14, v22
	v_mul_f32_e32 v22, v10, v25
	v_fmac_f32_e32 v22, v8, v4
	v_mul_f32_e32 v4, v10, v5
	v_lshlrev_b32_e32 v26, 16, v6
	v_fmac_f32_e32 v4, v8, v25
	v_fmac_f32_e32 v4, v12, v26
	v_add_f32_e32 v33, v14, v4
	v_mul_f32_e32 v4, v10, v26
	v_and_b32_e32 v6, 0xffff0000, v6
	v_fmac_f32_e32 v4, v8, v5
	v_fmac_f32_e32 v4, v12, v6
	v_add_f32_e32 v34, v14, v4
	v_mul_f32_e32 v4, v10, v6
	v_lshlrev_b32_e32 v27, 16, v7
	v_fmac_f32_e32 v4, v8, v26
	v_fmac_f32_e32 v4, v12, v27
	v_add_f32_e32 v35, v14, v4
	v_mul_f32_e32 v4, v10, v27
	v_and_b32_e32 v7, 0xffff0000, v7
	v_fmac_f32_e32 v4, v8, v6
	v_fmac_f32_e32 v4, v12, v7
	v_add_f32_e32 v36, v14, v4
	v_mul_f32_e32 v4, v10, v7
	v_fmac_f32_e32 v4, v8, v27
	v_fmac_f32_e32 v4, v12, v11
	v_add_f32_e32 v11, v14, v4
	s_waitcnt vmcnt(0)
	v_and_b32_e32 v4, 0xffff0000, v0
	v_lshlrev_b32_e32 v7, 16, v0
	v_mov_b32_e32 v6, v4
	v_pk_mul_f32 v[24:25], v[16:17], v[6:7]
	v_fmac_f32_e32 v22, v12, v5
	v_and_b32_e32 v5, 16, v0
	v_fma_f32 v0, v9, v13, v25
	v_add_f32_e32 v13, v24, v0
	v_and_b32_e32 v24, 0xffff0000, v1
	v_and_b32_e32 v25, 16, v1
	v_lshlrev_b32_e32 v1, 16, v1
	v_mov_b32_e32 v0, v24
	v_pk_mov_b32 v[26:27], v[0:1], v[4:5] op_sel:[1,0]
	v_add_f32_e32 v32, v14, v22
	v_pk_mul_f32 v[26:27], v[16:17], v[26:27]
	v_add_f32_e32 v13, v15, v13
	v_fma_f32 v5, v9, v7, v27
	v_pk_mul_f32 v[6:7], v[16:17], v[0:1]
	v_add_f32_e32 v37, v26, v5
	v_fma_f32 v0, v9, v4, v7
	v_and_b32_e32 v4, 0xffff0000, v2
	v_add_f32_e32 v38, v6, v0
	v_lshlrev_b32_e32 v7, 16, v2
	v_mov_b32_e32 v6, v4
	v_pk_mov_b32 v[26:27], v[6:7], v[24:25] op_sel:[1,0]
	v_and_b32_e32 v5, 16, v2
	v_pk_mul_f32 v[26:27], v[16:17], v[26:27]
	v_add_f32_e32 v37, v15, v37
	v_fma_f32 v0, v9, v1, v27
	v_add_f32_e32 v39, v26, v0
	v_pk_mul_f32 v[0:1], v[16:17], v[6:7]
	v_add_f32_e32 v38, v15, v38
	v_fma_f32 v1, v9, v24, v1
	v_add_f32_e32 v40, v0, v1
	v_and_b32_e32 v0, 0xffff0000, v3
	v_lshlrev_b32_e32 v1, 16, v3
	v_pk_mov_b32 v[2:3], v[0:1], v[4:5] op_sel:[1,0]
	v_mov_b32_e32 v22, v0
	v_pk_mul_f32 v[2:3], v[16:17], v[2:3]
	v_add_f32_e32 v39, v15, v39
	v_fma_f32 v3, v9, v7, v3
	v_add_f32_e32 v41, v2, v3
	v_pk_mul_f32 v[2:3], v[16:17], v[0:1]
	v_add_f32_e32 v40, v15, v40
	v_fma_f32 v3, v9, v4, v3
	v_add_f32_e32 v42, v2, v3
	v_pk_mul_f32 v[2:3], v[18:19], v[22:23]
	v_add_u32_e32 v22, 4, v20
	v_fma_f32 v0, v9, v1, v2
	v_add_u32_e32 v1, 2, v20
	v_add_f32_e32 v43, v0, v3
	v_xor_b32_e32 v0, v20, v108
	v_xor_b32_e32 v1, v1, v108
	v_lshl_add_u32 v0, v0, 3, 0
	v_lshl_add_u32 v4, v1, 3, 0
	ds_read_b128 v[0:3], v0
	ds_read_b128 v[4:7], v4
	v_add_u32_e32 v23, 6, v20
	v_xor_b32_e32 v22, v22, v108
	v_xor_b32_e32 v23, v23, v108
	v_lshl_add_u32 v22, v22, 3, 0
	v_lshl_add_u32 v26, v23, 3, 0
	ds_read_b128 v[22:25], v22
	ds_read_b128 v[26:29], v26
	s_waitcnt lgkmcnt(3)
	v_mul_f32_e32 v0, 0x38800000, v0
	v_mul_f32_e32 v0, v30, v0
	v_mul_f32_e32 v2, 0x38800000, v2
	v_mul_f32_e32 v2, v31, v2
	v_cvt_pk_bf16_f32 v30, v0, v2
	s_waitcnt lgkmcnt(2)
	v_mul_f32_e32 v0, 0x38800000, v4
	v_mul_f32_e32 v0, v32, v0
	v_mul_f32_e32 v2, 0x38800000, v6
	v_mul_f32_e32 v2, v33, v2
	v_cvt_pk_bf16_f32 v31, v0, v2
	s_waitcnt lgkmcnt(1)
	v_mul_f32_e32 v0, 0x38800000, v22
	v_mul_f32_e32 v0, v34, v0
	v_mul_f32_e32 v2, 0x38800000, v24
	v_mul_f32_e32 v2, v35, v2
	v_cvt_pk_bf16_f32 v32, v0, v2
	s_waitcnt lgkmcnt(0)
	v_mul_f32_e32 v0, 0x38800000, v26
	v_mul_f32_e32 v0, v36, v0
	v_mul_f32_e32 v2, 0x38800000, v28
	v_mul_f32_e32 v2, v11, v2
	v_cvt_pk_bf16_f32 v33, v0, v2
	v_mul_f32_e32 v0, 0x38800000, v1
	v_mul_f32_e32 v1, 0x38800000, v3
	v_mul_f32_e32 v0, v13, v0
	v_mul_f32_e32 v1, v37, v1
	v_cvt_pk_bf16_f32 v0, v0, v1
	v_mul_f32_e32 v1, 0x38800000, v5
	v_mul_f32_e32 v2, 0x38800000, v7
	v_mul_f32_e32 v1, v38, v1
	v_mul_f32_e32 v2, v39, v2
	v_add_f32_e32 v41, v15, v41
	v_cvt_pk_bf16_f32 v1, v1, v2
	v_mul_f32_e32 v2, 0x38800000, v23
	v_mul_f32_e32 v3, 0x38800000, v25
	v_mul_f32_e32 v2, v40, v2
	v_mul_f32_e32 v3, v41, v3
	v_add_f32_e32 v42, v15, v42
	v_add_f32_e32 v43, v15, v43
	v_cvt_pk_bf16_f32 v2, v2, v3
	v_mul_f32_e32 v3, 0x38800000, v27
	v_mul_f32_e32 v4, 0x38800000, v29
	v_mul_f32_e32 v3, v42, v3
	v_mul_f32_e32 v4, v43, v4
	v_cvt_pk_bf16_f32 v3, v3, v4
	v_lshlrev_b64 v[4:5], 1, v[20:21]
	v_lshl_add_u64 v[6:7], s[44:45], 0, v[4:5]
	v_lshl_add_u64 v[4:5], s[46:47], 0, v[4:5]
	global_store_dwordx4 v[6:7], v[30:33], off
	global_store_dwordx4 v[4:5], v[0:3], off

; __device__ __forceinline__ float bf2f(unsigned short u) { return __uint_as_float((unsigned)u << 16); }
; __device__ __forceinline__ float bflo(unsigned w) { return __uint_as_float(w << 16); }
; __device__ __forceinline__ float bfhi(unsigned w) { return __uint_as_float(w & 0xffff0000u); }
; __device__ __forceinline__ void sconv8(const bf16* urow, float w0, float w1, float w2, float b, int t0, float (&o)[8]) {
;     const u32x4 c = *(const u32x4*)(urow + t0);
;     const float um = t0 > 0 ? bf2f(urow[t0 - 1]) : 0.f, up = t0 + 8 < T_ ? bf2f(urow[t0 + 8]) : 0.f;
;     const float u[10] = {um, bflo(c.x), bfhi(c.x), bflo(c.y), bfhi(c.y), bflo(c.z), bfhi(c.z), bflo(c.w), bfhi(c.w), up};
; __device__ __forceinline__ void phase_fft(KA a, int l, LAS unsigned char* lds, int vcu, int G, int wave) {
;     ...
;             for (int i = 0; i < 3; ++i) { const int chk = tid + 512 * i, t0 = chk * 8;
;                 if (t0 < T_) {
;                     float zz0[8], zz1[8];
;                     sconv8(uv0, wv00, wv01, wv02, bv0, t0, zz0); { float tmp[8]; sconv8(ua0, wa00, wa01, wa02, ba0, t0, tmp);
; #pragma unroll
;                         for (int e = 0; e < 8; ++e) zz0[e] *= tmp[e]; }
;                     sconv8(uv1, wv10, wv11, wv12, bv1, t0, zz1); { float tmp[8]; sconv8(ua1, wa10, wa11, wa12, ba1, t0, tmp);
.LBB0_356:
	v_add_u32_e32 v20, s5, v107
	v_cmp_gt_i32_e32 vcc, s85, v20
	s_and_saveexec_b64 s[48:49], vcc
	s_cbranch_execz .LBB0_355
	v_mov_b32_e32 v140, 0
	v_mov_b32_e32 v141, 0
	v_mov_b32_e32 v142, 0
	v_mov_b32_e32 v143, 0
	v_ashrrev_i32_e32 v21, 31, v20
	v_lshl_add_u64 v[0:1], v[20:21], 1, s[42:43]
	global_load_dwordx4 v[4:7], v[0:1], off
	v_cmp_lt_i32_e32 vcc, 0, v20
	v_mov_b32_e32 v11, 0
	v_mov_b32_e32 v22, 0
	s_and_saveexec_b64 s[22:23], vcc
	s_cbranch_execz .LBB0_359
	v_mov_b32_e32 v148, v20
	v_lshl_add_u64 v[2:3], v[148:149], 1, s[42:43]
	global_load_ushort v140, v[2:3], off offset:-2
.LBB0_359:
	s_or_b64 exec, exec, s[22:23]
	s_movk_i32 s0, 0x2008
	v_cmp_gt_i32_e64 s[40:41], s0, v20
	s_and_saveexec_b64 s[22:23], s[40:41]
	s_cbranch_execz .LBB0_361
	global_load_ushort v141, v[0:1], off offset:16
.LBB0_361:
	s_or_b64 exec, exec, s[22:23]
	v_lshl_add_u64 v[24:25], v[20:21], 1, s[54:55]
	global_load_dwordx4 v[0:3], v[24:25], off
	v_mov_b32_e32 v23, 0
	v_mov_b32_e32 v13, 0
	s_and_saveexec_b64 s[22:23], vcc
	s_cbranch_execz .LBB0_363
	v_mov_b32_e32 v148, v20
	v_lshl_add_u64 v[26:27], v[148:149], 1, s[54:55]
	global_load_ushort v142, v[26:27], off offset:-2
.LBB0_363:
	s_or_b64 exec, exec, s[22:23]
	s_and_saveexec_b64 s[22:23], s[40:41]
	s_cbranch_execz .LBB0_354
	global_load_ushort v143, v[24:25], off offset:16
	s_branch .LBB0_354

; __device__ __forceinline__ unsigned pk2(float lo, float hi) { return pg8::cvt_pk_bf16(lo, hi); }
; __device__ __forceinline__ float bflo(unsigned w) { return __uint_as_float(w << 16); }
; __device__ __forceinline__ float bfhi(unsigned w) { return __uint_as_float(w & 0xffff0000u); }
; __device__ __forceinline__ void phase_lat(KA a, int l, int vcu, int G, int wave) {
;     ...
;     const float* gq = a->in[I_QLG] + l * QL; const float* gk = a->in[I_KVLG] + l * KVL;
;     for (int t = gw; t < T_; t += NGW) {
;         const bf16* row = (const bf16*)(a->ws + WS_ATT) + (size_t)t * 1024;
;         const u32x4 q = *(const u32x4*)(row + lane * 8); const u32x2 k = *(const u32x2*)(row + 512 + lane * 4);
;         float qv[8] = {bflo(q.x), bfhi(q.x), bflo(q.y), bfhi(q.y), bflo(q.z), bfhi(q.z), bflo(q.w), bfhi(q.w)};
;         float kv[4] = {bflo(k.x), bfhi(k.x), bflo(k.y), bfhi(k.y)};
;         float sq = 0.f, sk = 0.f;
; #pragma unroll
;         for (int e = 0; e < 8; ++e) sq += qv[e] * qv[e];
; #pragma unroll
;         for (int e = 0; e < 4; ++e) sk += kv[e] * kv[e];
;         sq = wave_sum(sq); sk = wave_sum(sk);
;         const float rq = rsqrtf(sq * (1.0f / QL) + EPS), rk = rsqrtf(sk * (1.0f / KVL) + EPS);
;         const f32x4 g0 = *(const f32x4*)(gq + lane * 8), g1 = *(const f32x4*)(gq + lane * 8 + 4), g2 = *(const f32x4*)(gk + lane * 4);
;         u32x4 wq; wq.x = pk2(qv[0] * rq * g0.x, qv[1] * rq * g0.y); wq.y = pk2(qv[2] * rq * g0.z, qv[3] * rq * g0.w);
;         wq.z = pk2(qv[4] * rq * g1.x, qv[5] * rq * g1.y); wq.w = pk2(qv[6] * rq * g1.z, qv[7] * rq * g1.w);
;         *(u32x4*)((bf16*)(a->ws + WS_CQN) + (size_t)t * QL + lane * 8) = wq;
;         u32x2 wk; wk.x = pk2(kv[0] * rk * g2.x, kv[1] * rk * g2.y); wk.y = pk2(kv[2] * rk * g2.z, kv[3] * rk * g2.w);
;         *(u32x2*)((bf16*)(a->ws + WS_CKVN) + (size_t)t * KVL + lane * 4) = wk;
;     }
.LBB0_425:
	s_andn2_b64 vcc, exec, s[22:23]
	s_mov_b64 s[46:47], 0
	s_cbranch_vccnz .LBB0_433
	s_cmp_gt_i32 s66, 0
	s_mov_b64 s[22:23], -1
	s_cbranch_scc0 .LBB0_431
	s_lshl_b32 s5, s81, 8
	s_add_i32 s5, s5, s11
	s_sub_i32 s5, s5, s81
	s_waitcnt lgkmcnt(0)
	s_add_i32 s42, s5, s81
	s_mov_b32 s0, 0x3b800000
	s_cmpk_lt_i32 s42, 0x2010
	s_mov_b32 s1, 0x3b000000
	s_mov_b32 s3, 0x800000
	v_mbcnt_lo_u32_b32 v0, -1, 0
	v_mbcnt_hi_u32_b32 v0, -1, v0
	s_cbranch_scc0 .LBB0_430
	v_and_b32_e32 v2, 63, v0
	v_and_b32_e32 v0, 64, v196
	v_add_u32_e32 v0, 64, v0
	v_xor_b32_e32 v1, 1, v196
	v_cmp_lt_i32_e32 vcc, v1, v0
	s_load_dwordx4 s[20:23], s[36:37], 0x20
	v_readlane_b32 s5, v254, 62
	v_cndmask_b32_e32 v1, v196, v1, vcc
	v_lshlrev_b32_e32 v26, 2, v1
	v_xor_b32_e32 v1, 2, v196
	v_cmp_lt_i32_e32 vcc, v1, v0
	s_lshl_b32 s24, s5, 8
	s_lshl_b32 s18, s5, 9
	v_cndmask_b32_e32 v1, v196, v1, vcc
	v_lshlrev_b32_e32 v27, 2, v1
	v_xor_b32_e32 v1, 4, v196
	v_cmp_lt_i32_e32 vcc, v1, v0
	s_ashr_i32 s25, s24, 31
	s_lshl_b32 s44, s15, 3
	v_cndmask_b32_e32 v1, v196, v1, vcc
	v_lshlrev_b32_e32 v28, 2, v1
	v_xor_b32_e32 v1, 8, v196
	v_cmp_lt_i32_e32 vcc, v1, v0
	s_ashr_i32 s19, s18, 31
	s_lshl_b64 s[24:25], s[24:25], 2
	v_cndmask_b32_e32 v1, v196, v1, vcc
	v_lshlrev_b32_e32 v29, 2, v1
	v_xor_b32_e32 v1, 16, v196
	v_cmp_lt_i32_e32 vcc, v1, v0
	s_waitcnt lgkmcnt(0)
	s_add_u32 s22, s22, s24
	s_addc_u32 s23, s23, s25
	v_cndmask_b32_e32 v1, v196, v1, vcc
	v_lshlrev_b32_e32 v30, 2, v1
	v_xor_b32_e32 v1, 32, v196
	s_lshl_b64 s[18:19], s[18:19], 2
	v_cmp_lt_i32_e32 vcc, v1, v0
	s_add_u32 s18, s20, s18
	s_addc_u32 s19, s21, s19
	v_cndmask_b32_e32 v0, v196, v1, vcc
	v_lshlrev_b32_e32 v31, 2, v0
	v_lshlrev_b32_e32 v0, 5, v2
	v_mov_b32_e32 v1, v149
	s_ashr_i32 s43, s42, 31
	v_lshl_add_u64 v[0:1], s[18:19], 0, v[0:1]
	s_lshl_b64 s[18:19], s[42:43], 9
	s_add_u32 s18, s16, s18
	v_lshlrev_b32_e32 v148, 3, v2
	s_addc_u32 s19, s17, s19
	v_lshl_add_u64 v[4:5], s[18:19], 0, v[148:149]
	s_mov_b64 s[18:19], 0x20450000
	s_ashr_i32 s45, s44, 31
	v_lshl_add_u64 v[4:5], v[4:5], 0, s[18:19]
	s_lshl_b64 s[46:47], s[44:45], 9
	s_lshl_b64 s[18:19], s[42:43], 10
	s_add_u32 s18, s16, s18
	v_lshlrev_b32_e32 v10, 4, v2
	v_mov_b32_e32 v11, v149
	s_addc_u32 s19, s17, s19
	v_lshl_add_u64 v[6:7], s[18:19], 0, v[10:11]
	s_mov_b64 s[18:19], 0x1fc10000
	v_lshl_add_u64 v[6:7], v[6:7], 0, s[18:19]
	s_lshl_b64 s[48:49], s[44:45], 10
	s_lshl_b64 s[18:19], s[42:43], 11
	s_add_u32 s5, s18, 0x1eb90400
	s_addc_u32 s7, s19, 0
	s_lshl_b64 s[52:53], s[44:45], 11
	s_waitcnt vmcnt(0)
	v_or_b32_e32 v8, s5, v148
	s_add_u32 s5, s18, 0x1eb90000
	v_mov_b32_e32 v9, s7
	s_addc_u32 s7, s19, 0
	v_lshl_add_u64 v[2:3], s[22:23], 0, v[10:11]
	v_or_b32_e32 v10, s5, v10
	v_mov_b32_e32 v11, s7
	s_mov_b64 s[54:55], s[16:17]
	global_load_dwordx4 v[64:67], v[0:1], off offset:16
	global_load_dwordx4 v[68:71], v[0:1], off
	global_load_dwordx4 v[72:75], v[2:3], off
.LBB0_429:
	v_lshl_add_u64 v[12:13], s[54:55], 0, v[10:11]
	global_load_dwordx4 v[32:35], v[12:13], off
	v_lshl_add_u64 v[12:13], s[54:55], 0, v[8:9]
	global_load_dwordx2 v[12:13], v[12:13], off
	s_add_i32 s42, s42, s44
	s_add_u32 s54, s54, s52
	s_addc_u32 s55, s55, s53
	s_cmpk_gt_i32 s42, 0x200f
	s_waitcnt vmcnt(1)
	v_lshlrev_b32_e32 v24, 16, v32
	v_and_b32_e32 v25, 0xffff0000, v32
	v_and_b32_e32 v20, 0xffff0000, v33
	v_lshlrev_b32_e32 v21, 16, v33
	v_and_b32_e32 v17, s0, v35
	v_and_b32_e32 v16, 0xffff0000, v34
	v_pk_mul_f32 v[32:33], v[24:25], v[24:25]
	v_pk_mul_f32 v[36:37], v[20:21], v[20:21]
	v_pk_mul_f32 v[38:39], v[16:17], v[16:17]
	v_add_f32_e32 v17, v32, v33
	v_add_f32_e32 v17, v37, v17
	v_lshlrev_b32_e32 v23, 16, v34
	v_mov_b32_e32 v22, v16
	s_waitcnt vmcnt(0)
	v_lshlrev_b32_e32 v14, 16, v12
	v_and_b32_e32 v15, 0xffff0000, v12
	v_add_f32_e32 v32, v36, v17
	v_and_b32_e32 v18, 0xffff0000, v35
	v_lshlrev_b32_e32 v19, 16, v35
	v_pk_mul_f32 v[40:41], v[14:15], v[14:15]
	v_and_b32_e32 v12, 0xffff0000, v13
	v_lshlrev_b32_e32 v13, 16, v13
	v_pk_fma_f32 v[32:33], v[22:23], v[22:23], v[32:33] op_sel_hi:[1,1,0]
	v_pk_mul_f32 v[34:35], v[18:19], v[18:19]
	v_pk_mul_f32 v[42:43], v[12:13], v[12:13]
	v_mov_b32_e32 v36, v40
	v_mov_b32_e32 v37, v38
	v_mov_b32_e32 v32, v41
	v_pk_add_f32 v[32:33], v[36:37], v[32:33]
	v_mov_b32_e32 v36, v43
	v_mov_b32_e32 v37, v35
	v_pk_add_f32 v[32:33], v[36:37], v[32:33]
	v_mov_b32_e32 v43, v34
	v_pk_add_f32 v[32:33], v[42:43], v[32:33]
	ds_bpermute_b32 v35, v26, v33
	ds_bpermute_b32 v34, v26, v32
	s_waitcnt lgkmcnt(0)
	v_pk_add_f32 v[32:33], v[32:33], v[34:35]
	ds_bpermute_b32 v35, v27, v33
	ds_bpermute_b32 v34, v27, v32
	s_waitcnt lgkmcnt(0)
	v_pk_add_f32 v[32:33], v[32:33], v[34:35]
	ds_bpermute_b32 v35, v28, v33
	ds_bpermute_b32 v34, v28, v32
	s_waitcnt lgkmcnt(0)
	v_pk_add_f32 v[32:33], v[32:33], v[34:35]
	ds_bpermute_b32 v35, v29, v33
	ds_bpermute_b32 v34, v29, v32
	s_waitcnt lgkmcnt(0)
	v_pk_add_f32 v[32:33], v[32:33], v[34:35]
	ds_bpermute_b32 v35, v30, v33
	ds_bpermute_b32 v34, v30, v32
	s_waitcnt lgkmcnt(0)
	v_pk_add_f32 v[32:33], v[32:33], v[34:35]
	ds_bpermute_b32 v35, v31, v33
	ds_bpermute_b32 v34, v31, v32
	s_waitcnt lgkmcnt(0)
	v_pk_add_f32 v[32:33], v[32:33], v[34:35]
	s_nop 0
	v_pk_fma_f32 v[32:33], v[32:33], s[0:1], v[154:155] op_sel_hi:[1,1,0]
	s_nop 0
	v_mul_f32_e32 v17, 0x4b800000, v33
	v_cmp_gt_f32_e64 s[40:41], s3, v33
	v_cmp_gt_f32_e32 vcc, s3, v32
	s_nop 0
	v_cndmask_b32_e64 v17, v33, v17, s[40:41]
	v_rsq_f32_e32 v17, v17
	s_nop 0
	v_mul_f32_e32 v22, 0x45800000, v17
	v_cndmask_b32_e64 v17, v17, v22, s[40:41]
	v_mul_f32_e32 v22, 0x4b800000, v32
	v_cndmask_b32_e32 v22, v32, v22, vcc
	v_rsq_f32_e32 v22, v22
	v_mul_f32_e32 v20, v17, v20
	v_mul_f32_e32 v24, v17, v24
	v_mul_f32_e32 v25, v17, v25
	v_mul_f32_e32 v32, 0x45800000, v22
	v_cndmask_b32_e32 v22, v22, v32, vcc
	v_mul_f32_e32 v21, v17, v21
	v_mul_f32_e32 v16, v17, v16
	v_mul_f32_e32 v14, v22, v14
	v_mul_f32_e32 v15, v22, v15
	v_mul_f32_e32 v13, v22, v13
	v_mul_f32_e32 v12, v22, v12
	v_mul_f32_e32 v16, v65, v16
	v_mul_f32_e32 v20, v71, v20
	v_mul_f32_e32 v24, v68, v24
	v_mul_f32_e32 v25, v69, v25
	v_cvt_pk_bf16_f32 v36, v24, v25
	v_mul_f32_e32 v21, v70, v21
	v_cvt_pk_bf16_f32 v37, v21, v20
	v_mul_f32_e32 v20, v17, v23
	v_mul_f32_e32 v20, v64, v20
	v_cvt_pk_bf16_f32 v38, v20, v16
	v_mul_f32_e32 v16, v17, v19
	v_mul_f32_e32 v17, v17, v18
	v_mul_f32_e32 v14, v72, v14
	v_mul_f32_e32 v15, v73, v15
	v_mul_f32_e32 v16, v66, v16
	v_mul_f32_e32 v17, v67, v17
	v_cvt_pk_bf16_f32 v39, v16, v17
	global_store_dwordx4 v[6:7], v[36:39], off
	s_nop 1
	v_cvt_pk_bf16_f32 v14, v14, v15
	v_mul_f32_e32 v13, v74, v13
	v_mul_f32_e32 v12, v75, v12
	v_cvt_pk_bf16_f32 v15, v13, v12
	global_store_dwordx2 v[4:5], v[14:15], off
	v_lshl_add_u64 v[4:5], v[4:5], 0, s[46:47]
	v_lshl_add_u64 v[6:7], v[6:7], 0, s[48:49]
	s_cbranch_scc0 .LBB0_429
